# GEMM epilogues of phases 9, 13, 16 software pipelined (residual rows loaded two row blocks ahead, counted vmcnt)
# speedup vs baseline: 1.0000x; 1.0000x over previous
.LBB0_2338:
	v_lshl_add_u32 v148, s26, 8, v137
	s_lshl_b32 s19, s6, 8
	s_ashr_i32 s21, s19, 31
	v_ashrrev_i32_e32 v149, 31, v148
	v_mov_b32_e32 v147, s21
	v_or_b32_e32 v146, s19, v136
	s_lshl_b32 s26, s6, 2
	s_ashr_i32 s27, s26, 31
	s_lshl_b32 s6, s47, 2
	v_readlane_b32 s56, v251, 8
	v_readlane_b32 s57, v251, 9
	v_readlane_b32 s58, v251, 10
	v_readlane_b32 s59, v251, 11
	v_readlane_b32 s60, v251, 12
	v_readlane_b32 s61, v251, 13
	v_readlane_b32 s62, v251, 14
	v_readlane_b32 s63, v251, 15
	v_readlane_b32 s64, v251, 16
	v_readlane_b32 s65, v251, 17
	v_readlane_b32 s66, v251, 18
	v_readlane_b32 s67, v251, 19
	v_readlane_b32 s68, v251, 20
	v_readlane_b32 s69, v251, 21
	v_readlane_b32 s70, v251, 22
	v_readlane_b32 s71, v251, 23
	v_mov_b32_e32 v212, v148
	v_ashrrev_i32_e32 v213, 31, v212
	v_lshlrev_b64 v[208:209], 10, v[212:213]
	v_lshl_add_u64 v[208:209], v[208:209], 0, v[146:147]
	v_lshl_add_u64 v[216:217], v[208:209], 2, s[56:57]
	global_load_dwordx4 v[172:175], v[216:217], off
	global_load_dwordx4 v[176:179], v[216:217], off offset:16
	global_load_dwordx4 v[180:183], v[216:217], off offset:512
	global_load_dwordx4 v[184:187], v[216:217], off offset:528
	v_or_b32_e32 v214, 16, v148
	v_ashrrev_i32_e32 v215, 31, v214
	v_lshlrev_b64 v[210:211], 10, v[214:215]
	v_lshl_add_u64 v[210:211], v[210:211], 0, v[146:147]
	v_lshl_add_u64 v[216:217], v[210:211], 2, s[56:57]
	global_load_dwordx4 v[188:191], v[216:217], off
	global_load_dwordx4 v[192:195], v[216:217], off offset:16
	global_load_dwordx4 v[196:199], v[216:217], off offset:512
	global_load_dwordx4 v[204:207], v[216:217], off offset:528
	s_waitcnt vmcnt(4)
	v_lshlrev_b64 v[164:165], 1, v[208:209]
	v_or_b32_e32 v166, 0x100, v164
	v_mov_b32_e32 v167, v165
	v_lshl_add_u64 v[164:165], s[10:11], 0, v[164:165]
	v_lshl_add_u64 v[166:167], s[10:11], 0, v[166:167]
	v_pk_add_f32 v[174:175], v[126:127], v[174:175]
	v_pk_add_f32 v[172:173], v[124:125], v[172:173]
	v_pk_add_f32 v[178:179], v[122:123], v[178:179]
	v_pk_add_f32 v[176:177], v[120:121], v[176:177]
	v_cvt_pk_bf16_f32 v156, v172, v173
	v_cvt_pk_bf16_f32 v157, v174, v175
	v_cvt_pk_bf16_f32 v158, v176, v177
	v_cvt_pk_bf16_f32 v159, v178, v179
	global_store_dwordx4 v[164:165], v[156:159], off
	v_mul_f32_e32 v173, v173, v173
	v_mul_f32_e32 v175, v175, v175
	v_mul_f32_e32 v177, v177, v177
	v_mul_f32_e32 v179, v179, v179
	v_fmac_f32_e32 v173, v172, v172
	v_fmac_f32_e32 v175, v174, v174
	v_fmac_f32_e32 v177, v176, v176
	v_fmac_f32_e32 v179, v178, v178
	v_add_f32_e32 v172, v173, v175
	v_add_f32_e32 v173, v177, v179
	v_add_f32_e32 v174, v172, v173
	v_pk_add_f32 v[182:183], v[118:119], v[182:183]
	v_pk_add_f32 v[180:181], v[116:117], v[180:181]
	v_pk_add_f32 v[186:187], v[114:115], v[186:187]
	v_pk_add_f32 v[184:185], v[112:113], v[184:185]
	v_cvt_pk_bf16_f32 v160, v180, v181
	v_cvt_pk_bf16_f32 v161, v182, v183
	v_cvt_pk_bf16_f32 v162, v184, v185
	v_cvt_pk_bf16_f32 v163, v186, v187
	global_store_dwordx4 v[166:167], v[160:163], off
	v_mul_f32_e32 v181, v181, v181
	v_mul_f32_e32 v183, v183, v183
	v_mul_f32_e32 v185, v185, v185
	v_mul_f32_e32 v187, v187, v187
	v_fmac_f32_e32 v181, v180, v180
	v_fmac_f32_e32 v183, v182, v182
	v_fmac_f32_e32 v185, v184, v184
	v_fmac_f32_e32 v187, v186, v186
	v_add_f32_e32 v180, v181, v183
	v_add_f32_e32 v181, v185, v187
	v_add_f32_e32 v182, v180, v181
	v_add_f32_e32 v168, v174, v182
	v_mov_b32_e32 v169, v168
	s_nop 1
	v_permlane16_swap_b32_e32 v168, v169
	v_add_f32_e32 v168, v168, v169
	v_mov_b32_e32 v169, v168
	s_nop 1
	v_permlane32_swap_b32_e32 v168, v169
	s_and_saveexec_b64 s[28:29], s[2:3]
	v_lshlrev_b64 v[216:217], 6, v[212:213]
	v_lshl_add_u64 v[216:217], s[12:13], 0, v[216:217]
	v_lshl_add_u64 v[216:217], s[26:27], 2, v[216:217]
	v_lshl_add_u64 v[216:217], v[216:217], 0, s[6:7]
	v_add_f32_e32 v168, v168, v169
	global_store_dword v[216:217], v168, off
	s_or_b64 exec, exec, s[28:29]
	v_or_b32_e32 v212, 32, v148
	v_ashrrev_i32_e32 v213, 31, v212
	v_lshlrev_b64 v[208:209], 10, v[212:213]
	v_lshl_add_u64 v[208:209], v[208:209], 0, v[146:147]
	v_lshl_add_u64 v[216:217], v[208:209], 2, s[56:57]
	global_load_dwordx4 v[172:175], v[216:217], off
	global_load_dwordx4 v[176:179], v[216:217], off offset:16
	global_load_dwordx4 v[180:183], v[216:217], off offset:512
	global_load_dwordx4 v[184:187], v[216:217], off offset:528
	s_waitcnt vmcnt(7)
	v_lshlrev_b64 v[164:165], 1, v[210:211]
	v_or_b32_e32 v166, 0x100, v164
	v_mov_b32_e32 v167, v165
	v_lshl_add_u64 v[164:165], s[10:11], 0, v[164:165]
	v_lshl_add_u64 v[166:167], s[10:11], 0, v[166:167]
	v_pk_add_f32 v[190:191], v[110:111], v[190:191]
	v_pk_add_f32 v[188:189], v[108:109], v[188:189]
	v_pk_add_f32 v[194:195], v[106:107], v[194:195]
	v_pk_add_f32 v[192:193], v[104:105], v[192:193]
	v_cvt_pk_bf16_f32 v156, v188, v189
	v_cvt_pk_bf16_f32 v157, v190, v191
	v_cvt_pk_bf16_f32 v158, v192, v193
	v_cvt_pk_bf16_f32 v159, v194, v195
	global_store_dwordx4 v[164:165], v[156:159], off
	v_mul_f32_e32 v189, v189, v189
	v_mul_f32_e32 v191, v191, v191
	v_mul_f32_e32 v193, v193, v193
	v_mul_f32_e32 v195, v195, v195
	v_fmac_f32_e32 v189, v188, v188
	v_fmac_f32_e32 v191, v190, v190
	v_fmac_f32_e32 v193, v192, v192
	v_fmac_f32_e32 v195, v194, v194
	v_add_f32_e32 v188, v189, v191
	v_add_f32_e32 v189, v193, v195
	v_add_f32_e32 v190, v188, v189
	v_pk_add_f32 v[198:199], v[102:103], v[198:199]
	v_pk_add_f32 v[196:197], v[100:101], v[196:197]
	v_pk_add_f32 v[206:207], v[98:99], v[206:207]
	v_pk_add_f32 v[204:205], v[96:97], v[204:205]
	v_cvt_pk_bf16_f32 v160, v196, v197
	v_cvt_pk_bf16_f32 v161, v198, v199
	v_cvt_pk_bf16_f32 v162, v204, v205
	v_cvt_pk_bf16_f32 v163, v206, v207
	global_store_dwordx4 v[166:167], v[160:163], off
	v_mul_f32_e32 v197, v197, v197
	v_mul_f32_e32 v199, v199, v199
	v_mul_f32_e32 v205, v205, v205
	v_mul_f32_e32 v207, v207, v207
	v_fmac_f32_e32 v197, v196, v196
	v_fmac_f32_e32 v199, v198, v198
	v_fmac_f32_e32 v205, v204, v204
	v_fmac_f32_e32 v207, v206, v206
	v_add_f32_e32 v196, v197, v199
	v_add_f32_e32 v197, v205, v207
	v_add_f32_e32 v198, v196, v197
	v_add_f32_e32 v168, v190, v198
	v_mov_b32_e32 v169, v168
	s_nop 1
	v_permlane16_swap_b32_e32 v168, v169
	v_add_f32_e32 v168, v168, v169
	v_mov_b32_e32 v169, v168
	s_nop 1
	v_permlane32_swap_b32_e32 v168, v169
	s_and_saveexec_b64 s[28:29], s[2:3]
	v_lshlrev_b64 v[216:217], 6, v[214:215]
	v_lshl_add_u64 v[216:217], s[12:13], 0, v[216:217]
	v_lshl_add_u64 v[216:217], s[26:27], 2, v[216:217]
	v_lshl_add_u64 v[216:217], v[216:217], 0, s[6:7]
	v_add_f32_e32 v168, v168, v169
	global_store_dword v[216:217], v168, off
	s_or_b64 exec, exec, s[28:29]
	v_or_b32_e32 v214, 48, v148
	v_ashrrev_i32_e32 v215, 31, v214
	v_lshlrev_b64 v[210:211], 10, v[214:215]
	v_lshl_add_u64 v[210:211], v[210:211], 0, v[146:147]
	v_lshl_add_u64 v[216:217], v[210:211], 2, s[56:57]
	global_load_dwordx4 v[188:191], v[216:217], off
	global_load_dwordx4 v[192:195], v[216:217], off offset:16
	global_load_dwordx4 v[196:199], v[216:217], off offset:512
	global_load_dwordx4 v[204:207], v[216:217], off offset:528
	s_waitcnt vmcnt(7)
	v_lshlrev_b64 v[164:165], 1, v[208:209]
	v_or_b32_e32 v166, 0x100, v164
	v_mov_b32_e32 v167, v165
	v_lshl_add_u64 v[164:165], s[10:11], 0, v[164:165]
	v_lshl_add_u64 v[166:167], s[10:11], 0, v[166:167]
	v_pk_add_f32 v[174:175], v[94:95], v[174:175]
	v_pk_add_f32 v[172:173], v[92:93], v[172:173]
	v_pk_add_f32 v[178:179], v[90:91], v[178:179]
	v_pk_add_f32 v[176:177], v[88:89], v[176:177]
	v_cvt_pk_bf16_f32 v156, v172, v173
	v_cvt_pk_bf16_f32 v157, v174, v175
	v_cvt_pk_bf16_f32 v158, v176, v177
	v_cvt_pk_bf16_f32 v159, v178, v179
	global_store_dwordx4 v[164:165], v[156:159], off
	v_mul_f32_e32 v173, v173, v173
	v_mul_f32_e32 v175, v175, v175
	v_mul_f32_e32 v177, v177, v177
	v_mul_f32_e32 v179, v179, v179
	v_fmac_f32_e32 v173, v172, v172
	v_fmac_f32_e32 v175, v174, v174
	v_fmac_f32_e32 v177, v176, v176
	v_fmac_f32_e32 v179, v178, v178
	v_add_f32_e32 v172, v173, v175
	v_add_f32_e32 v173, v177, v179
	v_add_f32_e32 v174, v172, v173
	v_pk_add_f32 v[182:183], v[86:87], v[182:183]
	v_pk_add_f32 v[180:181], v[84:85], v[180:181]
	v_pk_add_f32 v[186:187], v[82:83], v[186:187]
	v_pk_add_f32 v[184:185], v[80:81], v[184:185]
	v_cvt_pk_bf16_f32 v160, v180, v181
	v_cvt_pk_bf16_f32 v161, v182, v183
	v_cvt_pk_bf16_f32 v162, v184, v185
	v_cvt_pk_bf16_f32 v163, v186, v187
	global_store_dwordx4 v[166:167], v[160:163], off
	v_mul_f32_e32 v181, v181, v181
	v_mul_f32_e32 v183, v183, v183
	v_mul_f32_e32 v185, v185, v185
	v_mul_f32_e32 v187, v187, v187
	v_fmac_f32_e32 v181, v180, v180
	v_fmac_f32_e32 v183, v182, v182
	v_fmac_f32_e32 v185, v184, v184
	v_fmac_f32_e32 v187, v186, v186
	v_add_f32_e32 v180, v181, v183
	v_add_f32_e32 v181, v185, v187
	v_add_f32_e32 v182, v180, v181
	v_add_f32_e32 v168, v174, v182
	v_mov_b32_e32 v169, v168
	s_nop 1
	v_permlane16_swap_b32_e32 v168, v169
	v_add_f32_e32 v168, v168, v169
	v_mov_b32_e32 v169, v168
	s_nop 1
	v_permlane32_swap_b32_e32 v168, v169
	s_and_saveexec_b64 s[28:29], s[2:3]
	v_lshlrev_b64 v[216:217], 6, v[212:213]
	v_lshl_add_u64 v[216:217], s[12:13], 0, v[216:217]
	v_lshl_add_u64 v[216:217], s[26:27], 2, v[216:217]
	v_lshl_add_u64 v[216:217], v[216:217], 0, s[6:7]
	v_add_f32_e32 v168, v168, v169
	global_store_dword v[216:217], v168, off
	s_or_b64 exec, exec, s[28:29]
	v_add_u32_e32 v212, 0x80, v148
	v_ashrrev_i32_e32 v213, 31, v212
	v_lshlrev_b64 v[208:209], 10, v[212:213]
	v_lshl_add_u64 v[208:209], v[208:209], 0, v[146:147]
	v_lshl_add_u64 v[216:217], v[208:209], 2, s[56:57]
	global_load_dwordx4 v[172:175], v[216:217], off
	global_load_dwordx4 v[176:179], v[216:217], off offset:16
	global_load_dwordx4 v[180:183], v[216:217], off offset:512
	global_load_dwordx4 v[184:187], v[216:217], off offset:528
	s_waitcnt vmcnt(7)
	v_lshlrev_b64 v[164:165], 1, v[210:211]
	v_or_b32_e32 v166, 0x100, v164
	v_mov_b32_e32 v167, v165
	v_lshl_add_u64 v[164:165], s[10:11], 0, v[164:165]
	v_lshl_add_u64 v[166:167], s[10:11], 0, v[166:167]
	v_pk_add_f32 v[190:191], v[78:79], v[190:191]
	v_pk_add_f32 v[188:189], v[76:77], v[188:189]
	v_pk_add_f32 v[194:195], v[74:75], v[194:195]
	v_pk_add_f32 v[192:193], v[72:73], v[192:193]
	v_cvt_pk_bf16_f32 v156, v188, v189
	v_cvt_pk_bf16_f32 v157, v190, v191
	v_cvt_pk_bf16_f32 v158, v192, v193
	v_cvt_pk_bf16_f32 v159, v194, v195
	global_store_dwordx4 v[164:165], v[156:159], off
	v_mul_f32_e32 v189, v189, v189
	v_mul_f32_e32 v191, v191, v191
	v_mul_f32_e32 v193, v193, v193
	v_mul_f32_e32 v195, v195, v195
	v_fmac_f32_e32 v189, v188, v188
	v_fmac_f32_e32 v191, v190, v190
	v_fmac_f32_e32 v193, v192, v192
	v_fmac_f32_e32 v195, v194, v194
	v_add_f32_e32 v188, v189, v191
	v_add_f32_e32 v189, v193, v195
	v_add_f32_e32 v190, v188, v189
	v_pk_add_f32 v[198:199], v[70:71], v[198:199]
	v_pk_add_f32 v[196:197], v[68:69], v[196:197]
	v_pk_add_f32 v[206:207], v[66:67], v[206:207]
	v_pk_add_f32 v[204:205], v[64:65], v[204:205]
	v_cvt_pk_bf16_f32 v160, v196, v197
	v_cvt_pk_bf16_f32 v161, v198, v199
	v_cvt_pk_bf16_f32 v162, v204, v205
	v_cvt_pk_bf16_f32 v163, v206, v207
	global_store_dwordx4 v[166:167], v[160:163], off
	v_mul_f32_e32 v197, v197, v197
	v_mul_f32_e32 v199, v199, v199
	v_mul_f32_e32 v205, v205, v205
	v_mul_f32_e32 v207, v207, v207
	v_fmac_f32_e32 v197, v196, v196
	v_fmac_f32_e32 v199, v198, v198
	v_fmac_f32_e32 v205, v204, v204
	v_fmac_f32_e32 v207, v206, v206
	v_add_f32_e32 v196, v197, v199
	v_add_f32_e32 v197, v205, v207
	v_add_f32_e32 v198, v196, v197
	v_add_f32_e32 v168, v190, v198
	v_mov_b32_e32 v169, v168
	s_nop 1
	v_permlane16_swap_b32_e32 v168, v169
	v_add_f32_e32 v168, v168, v169
	v_mov_b32_e32 v169, v168
	s_nop 1
	v_permlane32_swap_b32_e32 v168, v169
	s_and_saveexec_b64 s[28:29], s[2:3]
	v_lshlrev_b64 v[216:217], 6, v[214:215]
	v_lshl_add_u64 v[216:217], s[12:13], 0, v[216:217]
	v_lshl_add_u64 v[216:217], s[26:27], 2, v[216:217]
	v_lshl_add_u64 v[216:217], v[216:217], 0, s[6:7]
	v_add_f32_e32 v168, v168, v169
	global_store_dword v[216:217], v168, off
	s_or_b64 exec, exec, s[28:29]
	v_add_u32_e32 v214, 0x90, v148
	v_ashrrev_i32_e32 v215, 31, v214
	v_lshlrev_b64 v[210:211], 10, v[214:215]
	v_lshl_add_u64 v[210:211], v[210:211], 0, v[146:147]
	v_lshl_add_u64 v[216:217], v[210:211], 2, s[56:57]
	global_load_dwordx4 v[188:191], v[216:217], off
	global_load_dwordx4 v[192:195], v[216:217], off offset:16
	global_load_dwordx4 v[196:199], v[216:217], off offset:512
	global_load_dwordx4 v[204:207], v[216:217], off offset:528
	s_waitcnt vmcnt(7)
	v_lshlrev_b64 v[164:165], 1, v[208:209]
	v_or_b32_e32 v166, 0x100, v164
	v_mov_b32_e32 v167, v165
	v_lshl_add_u64 v[164:165], s[10:11], 0, v[164:165]
	v_lshl_add_u64 v[166:167], s[10:11], 0, v[166:167]
	v_pk_add_f32 v[174:175], v[62:63], v[174:175]
	v_pk_add_f32 v[172:173], v[60:61], v[172:173]
	v_pk_add_f32 v[178:179], v[58:59], v[178:179]
	v_pk_add_f32 v[176:177], v[56:57], v[176:177]
	v_cvt_pk_bf16_f32 v156, v172, v173
	v_cvt_pk_bf16_f32 v157, v174, v175
	v_cvt_pk_bf16_f32 v158, v176, v177
	v_cvt_pk_bf16_f32 v159, v178, v179
	global_store_dwordx4 v[164:165], v[156:159], off
	v_mul_f32_e32 v173, v173, v173
	v_mul_f32_e32 v175, v175, v175
	v_mul_f32_e32 v177, v177, v177
	v_mul_f32_e32 v179, v179, v179
	v_fmac_f32_e32 v173, v172, v172
	v_fmac_f32_e32 v175, v174, v174
	v_fmac_f32_e32 v177, v176, v176
	v_fmac_f32_e32 v179, v178, v178
	v_add_f32_e32 v172, v173, v175
	v_add_f32_e32 v173, v177, v179
	v_add_f32_e32 v174, v172, v173
	v_pk_add_f32 v[182:183], v[54:55], v[182:183]
	v_pk_add_f32 v[180:181], v[52:53], v[180:181]
	v_pk_add_f32 v[186:187], v[50:51], v[186:187]
	v_pk_add_f32 v[184:185], v[48:49], v[184:185]
	v_cvt_pk_bf16_f32 v160, v180, v181
	v_cvt_pk_bf16_f32 v161, v182, v183
	v_cvt_pk_bf16_f32 v162, v184, v185
	v_cvt_pk_bf16_f32 v163, v186, v187
	global_store_dwordx4 v[166:167], v[160:163], off
	v_mul_f32_e32 v181, v181, v181
	v_mul_f32_e32 v183, v183, v183
	v_mul_f32_e32 v185, v185, v185
	v_mul_f32_e32 v187, v187, v187
	v_fmac_f32_e32 v181, v180, v180
	v_fmac_f32_e32 v183, v182, v182
	v_fmac_f32_e32 v185, v184, v184
	v_fmac_f32_e32 v187, v186, v186
	v_add_f32_e32 v180, v181, v183
	v_add_f32_e32 v181, v185, v187
	v_add_f32_e32 v182, v180, v181
	v_add_f32_e32 v168, v174, v182
	v_mov_b32_e32 v169, v168
	s_nop 1
	v_permlane16_swap_b32_e32 v168, v169
	v_add_f32_e32 v168, v168, v169
	v_mov_b32_e32 v169, v168
	s_nop 1
	v_permlane32_swap_b32_e32 v168, v169
	s_and_saveexec_b64 s[28:29], s[2:3]
	v_lshlrev_b64 v[216:217], 6, v[212:213]
	v_lshl_add_u64 v[216:217], s[12:13], 0, v[216:217]
	v_lshl_add_u64 v[216:217], s[26:27], 2, v[216:217]
	v_lshl_add_u64 v[216:217], v[216:217], 0, s[6:7]
	v_add_f32_e32 v168, v168, v169
	global_store_dword v[216:217], v168, off
	s_or_b64 exec, exec, s[28:29]
	v_add_u32_e32 v212, 0xa0, v148
	v_ashrrev_i32_e32 v213, 31, v212
	v_lshlrev_b64 v[208:209], 10, v[212:213]
	v_lshl_add_u64 v[208:209], v[208:209], 0, v[146:147]
	v_lshl_add_u64 v[216:217], v[208:209], 2, s[56:57]
	global_load_dwordx4 v[172:175], v[216:217], off
	global_load_dwordx4 v[176:179], v[216:217], off offset:16
	global_load_dwordx4 v[180:183], v[216:217], off offset:512
	global_load_dwordx4 v[184:187], v[216:217], off offset:528
	s_waitcnt vmcnt(7)
	v_lshlrev_b64 v[164:165], 1, v[210:211]
	v_or_b32_e32 v166, 0x100, v164
	v_mov_b32_e32 v167, v165
	v_lshl_add_u64 v[164:165], s[10:11], 0, v[164:165]
	v_lshl_add_u64 v[166:167], s[10:11], 0, v[166:167]
	v_pk_add_f32 v[190:191], v[46:47], v[190:191]
	v_pk_add_f32 v[188:189], v[44:45], v[188:189]
	v_pk_add_f32 v[194:195], v[42:43], v[194:195]
	v_pk_add_f32 v[192:193], v[40:41], v[192:193]
	v_cvt_pk_bf16_f32 v156, v188, v189
	v_cvt_pk_bf16_f32 v157, v190, v191
	v_cvt_pk_bf16_f32 v158, v192, v193
	v_cvt_pk_bf16_f32 v159, v194, v195
	global_store_dwordx4 v[164:165], v[156:159], off
	v_mul_f32_e32 v189, v189, v189
	v_mul_f32_e32 v191, v191, v191
	v_mul_f32_e32 v193, v193, v193
	v_mul_f32_e32 v195, v195, v195
	v_fmac_f32_e32 v189, v188, v188
	v_fmac_f32_e32 v191, v190, v190
	v_fmac_f32_e32 v193, v192, v192
	v_fmac_f32_e32 v195, v194, v194
	v_add_f32_e32 v188, v189, v191
	v_add_f32_e32 v189, v193, v195
	v_add_f32_e32 v190, v188, v189
	v_pk_add_f32 v[198:199], v[38:39], v[198:199]
	v_pk_add_f32 v[196:197], v[36:37], v[196:197]
	v_pk_add_f32 v[206:207], v[34:35], v[206:207]
	v_pk_add_f32 v[204:205], v[32:33], v[204:205]
	v_cvt_pk_bf16_f32 v160, v196, v197
	v_cvt_pk_bf16_f32 v161, v198, v199
	v_cvt_pk_bf16_f32 v162, v204, v205
	v_cvt_pk_bf16_f32 v163, v206, v207
	global_store_dwordx4 v[166:167], v[160:163], off
	v_mul_f32_e32 v197, v197, v197
	v_mul_f32_e32 v199, v199, v199
	v_mul_f32_e32 v205, v205, v205
	v_mul_f32_e32 v207, v207, v207
	v_fmac_f32_e32 v197, v196, v196
	v_fmac_f32_e32 v199, v198, v198
	v_fmac_f32_e32 v205, v204, v204
	v_fmac_f32_e32 v207, v206, v206
	v_add_f32_e32 v196, v197, v199
	v_add_f32_e32 v197, v205, v207
	v_add_f32_e32 v198, v196, v197
	v_add_f32_e32 v168, v190, v198
	v_mov_b32_e32 v169, v168
	s_nop 1
	v_permlane16_swap_b32_e32 v168, v169
	v_add_f32_e32 v168, v168, v169
	v_mov_b32_e32 v169, v168
	s_nop 1
	v_permlane32_swap_b32_e32 v168, v169
	s_and_saveexec_b64 s[28:29], s[2:3]
	v_lshlrev_b64 v[216:217], 6, v[214:215]
	v_lshl_add_u64 v[216:217], s[12:13], 0, v[216:217]
	v_lshl_add_u64 v[216:217], s[26:27], 2, v[216:217]
	v_lshl_add_u64 v[216:217], v[216:217], 0, s[6:7]
	v_add_f32_e32 v168, v168, v169
	global_store_dword v[216:217], v168, off
	s_or_b64 exec, exec, s[28:29]
	v_add_u32_e32 v214, 0xb0, v148
	v_ashrrev_i32_e32 v215, 31, v214
	v_lshlrev_b64 v[210:211], 10, v[214:215]
	v_lshl_add_u64 v[210:211], v[210:211], 0, v[146:147]
	v_lshl_add_u64 v[216:217], v[210:211], 2, s[56:57]
	global_load_dwordx4 v[188:191], v[216:217], off
	global_load_dwordx4 v[192:195], v[216:217], off offset:16
	global_load_dwordx4 v[196:199], v[216:217], off offset:512
	global_load_dwordx4 v[204:207], v[216:217], off offset:528
	s_waitcnt vmcnt(7)
	v_lshlrev_b64 v[164:165], 1, v[208:209]
	v_or_b32_e32 v166, 0x100, v164
	v_mov_b32_e32 v167, v165
	v_lshl_add_u64 v[164:165], s[10:11], 0, v[164:165]
	v_lshl_add_u64 v[166:167], s[10:11], 0, v[166:167]
	v_pk_add_f32 v[174:175], v[30:31], v[174:175]
	v_pk_add_f32 v[172:173], v[28:29], v[172:173]
	v_pk_add_f32 v[178:179], v[26:27], v[178:179]
	v_pk_add_f32 v[176:177], v[24:25], v[176:177]
	v_cvt_pk_bf16_f32 v156, v172, v173
	v_cvt_pk_bf16_f32 v157, v174, v175
	v_cvt_pk_bf16_f32 v158, v176, v177
	v_cvt_pk_bf16_f32 v159, v178, v179
	global_store_dwordx4 v[164:165], v[156:159], off
	v_mul_f32_e32 v173, v173, v173
	v_mul_f32_e32 v175, v175, v175
	v_mul_f32_e32 v177, v177, v177
	v_mul_f32_e32 v179, v179, v179
	v_fmac_f32_e32 v173, v172, v172
	v_fmac_f32_e32 v175, v174, v174
	v_fmac_f32_e32 v177, v176, v176
	v_fmac_f32_e32 v179, v178, v178
	v_add_f32_e32 v172, v173, v175
	v_add_f32_e32 v173, v177, v179
	v_add_f32_e32 v174, v172, v173
	v_pk_add_f32 v[182:183], v[22:23], v[182:183]
	v_pk_add_f32 v[180:181], v[20:21], v[180:181]
	v_pk_add_f32 v[186:187], v[18:19], v[186:187]
	v_pk_add_f32 v[184:185], v[16:17], v[184:185]
	v_cvt_pk_bf16_f32 v160, v180, v181
	v_cvt_pk_bf16_f32 v161, v182, v183
	v_cvt_pk_bf16_f32 v162, v184, v185
	v_cvt_pk_bf16_f32 v163, v186, v187
	global_store_dwordx4 v[166:167], v[160:163], off
	v_mul_f32_e32 v181, v181, v181
	v_mul_f32_e32 v183, v183, v183
	v_mul_f32_e32 v185, v185, v185
	v_mul_f32_e32 v187, v187, v187
	v_fmac_f32_e32 v181, v180, v180
	v_fmac_f32_e32 v183, v182, v182
	v_fmac_f32_e32 v185, v184, v184
	v_fmac_f32_e32 v187, v186, v186
	v_add_f32_e32 v180, v181, v183
	v_add_f32_e32 v181, v185, v187
	v_add_f32_e32 v182, v180, v181
	v_add_f32_e32 v168, v174, v182
	v_mov_b32_e32 v169, v168
	s_nop 1
	v_permlane16_swap_b32_e32 v168, v169
	v_add_f32_e32 v168, v168, v169
	v_mov_b32_e32 v169, v168
	s_nop 1
	v_permlane32_swap_b32_e32 v168, v169
	s_and_saveexec_b64 s[28:29], s[2:3]
	v_lshlrev_b64 v[216:217], 6, v[212:213]
	v_lshl_add_u64 v[216:217], s[12:13], 0, v[216:217]
	v_lshl_add_u64 v[216:217], s[26:27], 2, v[216:217]
	v_lshl_add_u64 v[216:217], v[216:217], 0, s[6:7]
	v_add_f32_e32 v168, v168, v169
	global_store_dword v[216:217], v168, off
	s_or_b64 exec, exec, s[28:29]
	s_waitcnt vmcnt(3)
	v_lshlrev_b64 v[164:165], 1, v[210:211]
	v_or_b32_e32 v166, 0x100, v164
	v_mov_b32_e32 v167, v165
	v_lshl_add_u64 v[164:165], s[10:11], 0, v[164:165]
	v_lshl_add_u64 v[166:167], s[10:11], 0, v[166:167]
	v_pk_add_f32 v[190:191], v[14:15], v[190:191]
	v_pk_add_f32 v[188:189], v[12:13], v[188:189]
	v_pk_add_f32 v[194:195], v[10:11], v[194:195]
	v_pk_add_f32 v[192:193], v[8:9], v[192:193]
	v_cvt_pk_bf16_f32 v156, v188, v189
	v_cvt_pk_bf16_f32 v157, v190, v191
	v_cvt_pk_bf16_f32 v158, v192, v193
	v_cvt_pk_bf16_f32 v159, v194, v195
	global_store_dwordx4 v[164:165], v[156:159], off
	v_mul_f32_e32 v189, v189, v189
	v_mul_f32_e32 v191, v191, v191
	v_mul_f32_e32 v193, v193, v193
	v_mul_f32_e32 v195, v195, v195
	v_fmac_f32_e32 v189, v188, v188
	v_fmac_f32_e32 v191, v190, v190
	v_fmac_f32_e32 v193, v192, v192
	v_fmac_f32_e32 v195, v194, v194
	v_add_f32_e32 v188, v189, v191
	v_add_f32_e32 v189, v193, v195
	v_add_f32_e32 v190, v188, v189
	v_pk_add_f32 v[198:199], v[6:7], v[198:199]
	v_pk_add_f32 v[196:197], v[4:5], v[196:197]
	v_pk_add_f32 v[206:207], v[2:3], v[206:207]
	v_pk_add_f32 v[204:205], v[0:1], v[204:205]
	v_cvt_pk_bf16_f32 v160, v196, v197
	v_cvt_pk_bf16_f32 v161, v198, v199
	v_cvt_pk_bf16_f32 v162, v204, v205
	v_cvt_pk_bf16_f32 v163, v206, v207
	global_store_dwordx4 v[166:167], v[160:163], off
	v_mul_f32_e32 v197, v197, v197
	v_mul_f32_e32 v199, v199, v199
	v_mul_f32_e32 v205, v205, v205
	v_mul_f32_e32 v207, v207, v207
	v_fmac_f32_e32 v197, v196, v196
	v_fmac_f32_e32 v199, v198, v198
	v_fmac_f32_e32 v205, v204, v204
	v_fmac_f32_e32 v207, v206, v206
	v_add_f32_e32 v196, v197, v199
	v_add_f32_e32 v197, v205, v207
	v_add_f32_e32 v198, v196, v197
	v_add_f32_e32 v168, v190, v198
	v_mov_b32_e32 v169, v168
	s_nop 1
	v_permlane16_swap_b32_e32 v168, v169
	v_add_f32_e32 v168, v168, v169
	v_mov_b32_e32 v169, v168
	s_nop 1
	v_permlane32_swap_b32_e32 v168, v169
	s_and_saveexec_b64 s[28:29], s[2:3]
	v_lshlrev_b64 v[216:217], 6, v[214:215]
	v_lshl_add_u64 v[216:217], s[12:13], 0, v[216:217]
	v_lshl_add_u64 v[216:217], s[26:27], 2, v[216:217]
	v_lshl_add_u64 v[216:217], v[216:217], 0, s[6:7]
	v_add_f32_e32 v168, v168, v169
	global_store_dword v[216:217], v168, off
	s_or_b64 exec, exec, s[28:29]

.LBB0_2569:
	v_lshl_add_u32 v148, s26, 8, v137
	s_lshl_b32 s19, s6, 8
	s_ashr_i32 s21, s19, 31
	v_ashrrev_i32_e32 v149, 31, v148
	v_mov_b32_e32 v147, s21
	v_or_b32_e32 v146, s19, v136
	s_lshl_b32 s26, s6, 2
	s_ashr_i32 s27, s26, 31
	s_lshl_b32 s6, s47, 2
	v_mov_b32_e32 v204, v148
	v_ashrrev_i32_e32 v205, 31, v204
	v_lshlrev_b64 v[196:197], 10, v[204:205]
	v_lshl_add_u64 v[196:197], v[196:197], 0, v[146:147]
	v_lshl_add_u64 v[208:209], v[196:197], 1, s[10:11]
	global_load_dwordx4 v[172:175], v[208:209], off
	global_load_dwordx4 v[176:179], v[208:209], off offset:256
	v_or_b32_e32 v206, 16, v148
	v_ashrrev_i32_e32 v207, 31, v206
	v_lshlrev_b64 v[198:199], 10, v[206:207]
	v_lshl_add_u64 v[198:199], v[198:199], 0, v[146:147]
	v_lshl_add_u64 v[208:209], v[198:199], 1, s[10:11]
	global_load_dwordx4 v[180:183], v[208:209], off
	global_load_dwordx4 v[184:187], v[208:209], off offset:256
	s_waitcnt vmcnt(2)
	v_lshlrev_b32_e32 v156, 16, v172
	v_and_b32_e32 v157, 0xffff0000, v172
	v_lshlrev_b32_e32 v158, 16, v173
	v_and_b32_e32 v159, 0xffff0000, v173
	v_lshlrev_b32_e32 v160, 16, v174
	v_and_b32_e32 v161, 0xffff0000, v174
	v_lshlrev_b32_e32 v162, 16, v175
	v_and_b32_e32 v163, 0xffff0000, v175
	v_lshlrev_b32_e32 v164, 16, v176
	v_and_b32_e32 v165, 0xffff0000, v176
	v_lshlrev_b32_e32 v166, 16, v177
	v_and_b32_e32 v167, 0xffff0000, v177
	v_lshlrev_b32_e32 v168, 16, v178
	v_and_b32_e32 v169, 0xffff0000, v178
	v_lshlrev_b32_e32 v170, 16, v179
	v_and_b32_e32 v171, 0xffff0000, v179
	v_pk_add_f32 v[156:157], v[124:125], v[156:157]
	v_pk_add_f32 v[158:159], v[126:127], v[158:159]
	v_pk_add_f32 v[160:161], v[120:121], v[160:161]
	v_pk_add_f32 v[162:163], v[122:123], v[162:163]
	v_pk_add_f32 v[164:165], v[116:117], v[164:165]
	v_pk_add_f32 v[166:167], v[118:119], v[166:167]
	v_pk_add_f32 v[168:169], v[112:113], v[168:169]
	v_pk_add_f32 v[170:171], v[114:115], v[170:171]
	v_cvt_pk_bf16_f32 v188, v156, v157
	v_cvt_pk_bf16_f32 v189, v158, v159
	v_cvt_pk_bf16_f32 v190, v160, v161
	v_cvt_pk_bf16_f32 v191, v162, v163
	v_cvt_pk_bf16_f32 v192, v164, v165
	v_cvt_pk_bf16_f32 v193, v166, v167
	v_cvt_pk_bf16_f32 v194, v168, v169
	v_cvt_pk_bf16_f32 v195, v170, v171
	v_lshl_add_u64 v[210:211], v[196:197], 1, s[10:11]
	global_store_dwordx4 v[210:211], v[188:191], off
	global_store_dwordx4 v[210:211], v[192:195], off offset:256
	v_mul_f32_e32 v157, v157, v157
	v_mul_f32_e32 v159, v159, v159
	v_mul_f32_e32 v161, v161, v161
	v_mul_f32_e32 v163, v163, v163
	v_mul_f32_e32 v165, v165, v165
	v_mul_f32_e32 v167, v167, v167
	v_mul_f32_e32 v169, v169, v169
	v_mul_f32_e32 v171, v171, v171
	v_fmac_f32_e32 v157, v156, v156
	v_fmac_f32_e32 v159, v158, v158
	v_fmac_f32_e32 v161, v160, v160
	v_fmac_f32_e32 v163, v162, v162
	v_fmac_f32_e32 v165, v164, v164
	v_fmac_f32_e32 v167, v166, v166
	v_fmac_f32_e32 v169, v168, v168
	v_fmac_f32_e32 v171, v170, v170
	v_add_f32_e32 v156, v157, v159
	v_add_f32_e32 v158, v161, v163
	v_add_f32_e32 v164, v165, v167
	v_add_f32_e32 v166, v169, v171
	v_add_f32_e32 v156, v156, v158
	v_add_f32_e32 v164, v164, v166
	v_add_f32_e32 v212, v156, v164
	v_mov_b32_e32 v213, v212
	s_nop 1
	v_permlane16_swap_b32_e32 v212, v213
	v_add_f32_e32 v212, v212, v213
	v_mov_b32_e32 v213, v212
	s_nop 1
	v_permlane32_swap_b32_e32 v212, v213
	s_and_saveexec_b64 s[28:29], s[2:3]
	v_lshlrev_b64 v[214:215], 6, v[204:205]
	v_lshl_add_u64 v[214:215], s[12:13], 0, v[214:215]
	v_lshl_add_u64 v[214:215], s[26:27], 2, v[214:215]
	v_lshl_add_u64 v[214:215], v[214:215], 0, s[6:7]
	v_add_f32_e32 v212, v212, v213
	global_store_dword v[214:215], v212, off
	s_or_b64 exec, exec, s[28:29]
	v_or_b32_e32 v204, 32, v148
	v_ashrrev_i32_e32 v205, 31, v204
	v_lshlrev_b64 v[196:197], 10, v[204:205]
	v_lshl_add_u64 v[196:197], v[196:197], 0, v[146:147]
	v_lshl_add_u64 v[208:209], v[196:197], 1, s[10:11]
	global_load_dwordx4 v[172:175], v[208:209], off
	global_load_dwordx4 v[176:179], v[208:209], off offset:256
	s_waitcnt vmcnt(5)
	v_lshlrev_b32_e32 v156, 16, v180
	v_and_b32_e32 v157, 0xffff0000, v180
	v_lshlrev_b32_e32 v158, 16, v181
	v_and_b32_e32 v159, 0xffff0000, v181
	v_lshlrev_b32_e32 v160, 16, v182
	v_and_b32_e32 v161, 0xffff0000, v182
	v_lshlrev_b32_e32 v162, 16, v183
	v_and_b32_e32 v163, 0xffff0000, v183
	v_lshlrev_b32_e32 v164, 16, v184
	v_and_b32_e32 v165, 0xffff0000, v184
	v_lshlrev_b32_e32 v166, 16, v185
	v_and_b32_e32 v167, 0xffff0000, v185
	v_lshlrev_b32_e32 v168, 16, v186
	v_and_b32_e32 v169, 0xffff0000, v186
	v_lshlrev_b32_e32 v170, 16, v187
	v_and_b32_e32 v171, 0xffff0000, v187
	v_pk_add_f32 v[156:157], v[108:109], v[156:157]
	v_pk_add_f32 v[158:159], v[110:111], v[158:159]
	v_pk_add_f32 v[160:161], v[104:105], v[160:161]
	v_pk_add_f32 v[162:163], v[106:107], v[162:163]
	v_pk_add_f32 v[164:165], v[100:101], v[164:165]
	v_pk_add_f32 v[166:167], v[102:103], v[166:167]
	v_pk_add_f32 v[168:169], v[96:97], v[168:169]
	v_pk_add_f32 v[170:171], v[98:99], v[170:171]
	v_cvt_pk_bf16_f32 v188, v156, v157
	v_cvt_pk_bf16_f32 v189, v158, v159
	v_cvt_pk_bf16_f32 v190, v160, v161
	v_cvt_pk_bf16_f32 v191, v162, v163
	v_cvt_pk_bf16_f32 v192, v164, v165
	v_cvt_pk_bf16_f32 v193, v166, v167
	v_cvt_pk_bf16_f32 v194, v168, v169
	v_cvt_pk_bf16_f32 v195, v170, v171
	v_lshl_add_u64 v[210:211], v[198:199], 1, s[10:11]
	global_store_dwordx4 v[210:211], v[188:191], off
	global_store_dwordx4 v[210:211], v[192:195], off offset:256
	v_mul_f32_e32 v157, v157, v157
	v_mul_f32_e32 v159, v159, v159
	v_mul_f32_e32 v161, v161, v161
	v_mul_f32_e32 v163, v163, v163
	v_mul_f32_e32 v165, v165, v165
	v_mul_f32_e32 v167, v167, v167
	v_mul_f32_e32 v169, v169, v169
	v_mul_f32_e32 v171, v171, v171
	v_fmac_f32_e32 v157, v156, v156
	v_fmac_f32_e32 v159, v158, v158
	v_fmac_f32_e32 v161, v160, v160
	v_fmac_f32_e32 v163, v162, v162
	v_fmac_f32_e32 v165, v164, v164
	v_fmac_f32_e32 v167, v166, v166
	v_fmac_f32_e32 v169, v168, v168
	v_fmac_f32_e32 v171, v170, v170
	v_add_f32_e32 v156, v157, v159
	v_add_f32_e32 v158, v161, v163
	v_add_f32_e32 v164, v165, v167
	v_add_f32_e32 v166, v169, v171
	v_add_f32_e32 v156, v156, v158
	v_add_f32_e32 v164, v164, v166
	v_add_f32_e32 v212, v156, v164
	v_mov_b32_e32 v213, v212
	s_nop 1
	v_permlane16_swap_b32_e32 v212, v213
	v_add_f32_e32 v212, v212, v213
	v_mov_b32_e32 v213, v212
	s_nop 1
	v_permlane32_swap_b32_e32 v212, v213
	s_and_saveexec_b64 s[28:29], s[2:3]
	v_lshlrev_b64 v[214:215], 6, v[206:207]
	v_lshl_add_u64 v[214:215], s[12:13], 0, v[214:215]
	v_lshl_add_u64 v[214:215], s[26:27], 2, v[214:215]
	v_lshl_add_u64 v[214:215], v[214:215], 0, s[6:7]
	v_add_f32_e32 v212, v212, v213
	global_store_dword v[214:215], v212, off
	s_or_b64 exec, exec, s[28:29]
	v_or_b32_e32 v206, 48, v148
	v_ashrrev_i32_e32 v207, 31, v206
	v_lshlrev_b64 v[198:199], 10, v[206:207]
	v_lshl_add_u64 v[198:199], v[198:199], 0, v[146:147]
	v_lshl_add_u64 v[208:209], v[198:199], 1, s[10:11]
	global_load_dwordx4 v[180:183], v[208:209], off
	global_load_dwordx4 v[184:187], v[208:209], off offset:256
	s_waitcnt vmcnt(5)
	v_lshlrev_b32_e32 v156, 16, v172
	v_and_b32_e32 v157, 0xffff0000, v172
	v_lshlrev_b32_e32 v158, 16, v173
	v_and_b32_e32 v159, 0xffff0000, v173
	v_lshlrev_b32_e32 v160, 16, v174
	v_and_b32_e32 v161, 0xffff0000, v174
	v_lshlrev_b32_e32 v162, 16, v175
	v_and_b32_e32 v163, 0xffff0000, v175
	v_lshlrev_b32_e32 v164, 16, v176
	v_and_b32_e32 v165, 0xffff0000, v176
	v_lshlrev_b32_e32 v166, 16, v177
	v_and_b32_e32 v167, 0xffff0000, v177
	v_lshlrev_b32_e32 v168, 16, v178
	v_and_b32_e32 v169, 0xffff0000, v178
	v_lshlrev_b32_e32 v170, 16, v179
	v_and_b32_e32 v171, 0xffff0000, v179
	v_pk_add_f32 v[156:157], v[92:93], v[156:157]
	v_pk_add_f32 v[158:159], v[94:95], v[158:159]
	v_pk_add_f32 v[160:161], v[88:89], v[160:161]
	v_pk_add_f32 v[162:163], v[90:91], v[162:163]
	v_pk_add_f32 v[164:165], v[84:85], v[164:165]
	v_pk_add_f32 v[166:167], v[86:87], v[166:167]
	v_pk_add_f32 v[168:169], v[80:81], v[168:169]
	v_pk_add_f32 v[170:171], v[82:83], v[170:171]
	v_cvt_pk_bf16_f32 v188, v156, v157
	v_cvt_pk_bf16_f32 v189, v158, v159
	v_cvt_pk_bf16_f32 v190, v160, v161
	v_cvt_pk_bf16_f32 v191, v162, v163
	v_cvt_pk_bf16_f32 v192, v164, v165
	v_cvt_pk_bf16_f32 v193, v166, v167
	v_cvt_pk_bf16_f32 v194, v168, v169
	v_cvt_pk_bf16_f32 v195, v170, v171
	v_lshl_add_u64 v[210:211], v[196:197], 1, s[10:11]
	global_store_dwordx4 v[210:211], v[188:191], off
	global_store_dwordx4 v[210:211], v[192:195], off offset:256
	v_mul_f32_e32 v157, v157, v157
	v_mul_f32_e32 v159, v159, v159
	v_mul_f32_e32 v161, v161, v161
	v_mul_f32_e32 v163, v163, v163
	v_mul_f32_e32 v165, v165, v165
	v_mul_f32_e32 v167, v167, v167
	v_mul_f32_e32 v169, v169, v169
	v_mul_f32_e32 v171, v171, v171
	v_fmac_f32_e32 v157, v156, v156
	v_fmac_f32_e32 v159, v158, v158
	v_fmac_f32_e32 v161, v160, v160
	v_fmac_f32_e32 v163, v162, v162
	v_fmac_f32_e32 v165, v164, v164
	v_fmac_f32_e32 v167, v166, v166
	v_fmac_f32_e32 v169, v168, v168
	v_fmac_f32_e32 v171, v170, v170
	v_add_f32_e32 v156, v157, v159
	v_add_f32_e32 v158, v161, v163
	v_add_f32_e32 v164, v165, v167
	v_add_f32_e32 v166, v169, v171
	v_add_f32_e32 v156, v156, v158
	v_add_f32_e32 v164, v164, v166
	v_add_f32_e32 v212, v156, v164
	v_mov_b32_e32 v213, v212
	s_nop 1
	v_permlane16_swap_b32_e32 v212, v213
	v_add_f32_e32 v212, v212, v213
	v_mov_b32_e32 v213, v212
	s_nop 1
	v_permlane32_swap_b32_e32 v212, v213
	s_and_saveexec_b64 s[28:29], s[2:3]
	v_lshlrev_b64 v[214:215], 6, v[204:205]
	v_lshl_add_u64 v[214:215], s[12:13], 0, v[214:215]
	v_lshl_add_u64 v[214:215], s[26:27], 2, v[214:215]
	v_lshl_add_u64 v[214:215], v[214:215], 0, s[6:7]
	v_add_f32_e32 v212, v212, v213
	global_store_dword v[214:215], v212, off
	s_or_b64 exec, exec, s[28:29]
	v_add_u32_e32 v204, 0x80, v148
	v_ashrrev_i32_e32 v205, 31, v204
	v_lshlrev_b64 v[196:197], 10, v[204:205]
	v_lshl_add_u64 v[196:197], v[196:197], 0, v[146:147]
	v_lshl_add_u64 v[208:209], v[196:197], 1, s[10:11]
	global_load_dwordx4 v[172:175], v[208:209], off
	global_load_dwordx4 v[176:179], v[208:209], off offset:256
	s_waitcnt vmcnt(5)
	v_lshlrev_b32_e32 v156, 16, v180
	v_and_b32_e32 v157, 0xffff0000, v180
	v_lshlrev_b32_e32 v158, 16, v181
	v_and_b32_e32 v159, 0xffff0000, v181
	v_lshlrev_b32_e32 v160, 16, v182
	v_and_b32_e32 v161, 0xffff0000, v182
	v_lshlrev_b32_e32 v162, 16, v183
	v_and_b32_e32 v163, 0xffff0000, v183
	v_lshlrev_b32_e32 v164, 16, v184
	v_and_b32_e32 v165, 0xffff0000, v184
	v_lshlrev_b32_e32 v166, 16, v185
	v_and_b32_e32 v167, 0xffff0000, v185
	v_lshlrev_b32_e32 v168, 16, v186
	v_and_b32_e32 v169, 0xffff0000, v186
	v_lshlrev_b32_e32 v170, 16, v187
	v_and_b32_e32 v171, 0xffff0000, v187
	v_pk_add_f32 v[156:157], v[76:77], v[156:157]
	v_pk_add_f32 v[158:159], v[78:79], v[158:159]
	v_pk_add_f32 v[160:161], v[72:73], v[160:161]
	v_pk_add_f32 v[162:163], v[74:75], v[162:163]
	v_pk_add_f32 v[164:165], v[68:69], v[164:165]
	v_pk_add_f32 v[166:167], v[70:71], v[166:167]
	v_pk_add_f32 v[168:169], v[64:65], v[168:169]
	v_pk_add_f32 v[170:171], v[66:67], v[170:171]
	v_cvt_pk_bf16_f32 v188, v156, v157
	v_cvt_pk_bf16_f32 v189, v158, v159
	v_cvt_pk_bf16_f32 v190, v160, v161
	v_cvt_pk_bf16_f32 v191, v162, v163
	v_cvt_pk_bf16_f32 v192, v164, v165
	v_cvt_pk_bf16_f32 v193, v166, v167
	v_cvt_pk_bf16_f32 v194, v168, v169
	v_cvt_pk_bf16_f32 v195, v170, v171
	v_lshl_add_u64 v[210:211], v[198:199], 1, s[10:11]
	global_store_dwordx4 v[210:211], v[188:191], off
	global_store_dwordx4 v[210:211], v[192:195], off offset:256
	v_mul_f32_e32 v157, v157, v157
	v_mul_f32_e32 v159, v159, v159
	v_mul_f32_e32 v161, v161, v161
	v_mul_f32_e32 v163, v163, v163
	v_mul_f32_e32 v165, v165, v165
	v_mul_f32_e32 v167, v167, v167
	v_mul_f32_e32 v169, v169, v169
	v_mul_f32_e32 v171, v171, v171
	v_fmac_f32_e32 v157, v156, v156
	v_fmac_f32_e32 v159, v158, v158
	v_fmac_f32_e32 v161, v160, v160
	v_fmac_f32_e32 v163, v162, v162
	v_fmac_f32_e32 v165, v164, v164
	v_fmac_f32_e32 v167, v166, v166
	v_fmac_f32_e32 v169, v168, v168
	v_fmac_f32_e32 v171, v170, v170
	v_add_f32_e32 v156, v157, v159
	v_add_f32_e32 v158, v161, v163
	v_add_f32_e32 v164, v165, v167
	v_add_f32_e32 v166, v169, v171
	v_add_f32_e32 v156, v156, v158
	v_add_f32_e32 v164, v164, v166
	v_add_f32_e32 v212, v156, v164
	v_mov_b32_e32 v213, v212
	s_nop 1
	v_permlane16_swap_b32_e32 v212, v213
	v_add_f32_e32 v212, v212, v213
	v_mov_b32_e32 v213, v212
	s_nop 1
	v_permlane32_swap_b32_e32 v212, v213
	s_and_saveexec_b64 s[28:29], s[2:3]
	v_lshlrev_b64 v[214:215], 6, v[206:207]
	v_lshl_add_u64 v[214:215], s[12:13], 0, v[214:215]
	v_lshl_add_u64 v[214:215], s[26:27], 2, v[214:215]
	v_lshl_add_u64 v[214:215], v[214:215], 0, s[6:7]
	v_add_f32_e32 v212, v212, v213
	global_store_dword v[214:215], v212, off
	s_or_b64 exec, exec, s[28:29]
	v_add_u32_e32 v206, 0x90, v148
	v_ashrrev_i32_e32 v207, 31, v206
	v_lshlrev_b64 v[198:199], 10, v[206:207]
	v_lshl_add_u64 v[198:199], v[198:199], 0, v[146:147]
	v_lshl_add_u64 v[208:209], v[198:199], 1, s[10:11]
	global_load_dwordx4 v[180:183], v[208:209], off
	global_load_dwordx4 v[184:187], v[208:209], off offset:256
	s_waitcnt vmcnt(5)
	v_lshlrev_b32_e32 v156, 16, v172
	v_and_b32_e32 v157, 0xffff0000, v172
	v_lshlrev_b32_e32 v158, 16, v173
	v_and_b32_e32 v159, 0xffff0000, v173
	v_lshlrev_b32_e32 v160, 16, v174
	v_and_b32_e32 v161, 0xffff0000, v174
	v_lshlrev_b32_e32 v162, 16, v175
	v_and_b32_e32 v163, 0xffff0000, v175
	v_lshlrev_b32_e32 v164, 16, v176
	v_and_b32_e32 v165, 0xffff0000, v176
	v_lshlrev_b32_e32 v166, 16, v177
	v_and_b32_e32 v167, 0xffff0000, v177
	v_lshlrev_b32_e32 v168, 16, v178
	v_and_b32_e32 v169, 0xffff0000, v178
	v_lshlrev_b32_e32 v170, 16, v179
	v_and_b32_e32 v171, 0xffff0000, v179
	v_pk_add_f32 v[156:157], v[60:61], v[156:157]
	v_pk_add_f32 v[158:159], v[62:63], v[158:159]
	v_pk_add_f32 v[160:161], v[56:57], v[160:161]
	v_pk_add_f32 v[162:163], v[58:59], v[162:163]
	v_pk_add_f32 v[164:165], v[52:53], v[164:165]
	v_pk_add_f32 v[166:167], v[54:55], v[166:167]
	v_pk_add_f32 v[168:169], v[48:49], v[168:169]
	v_pk_add_f32 v[170:171], v[50:51], v[170:171]
	v_cvt_pk_bf16_f32 v188, v156, v157
	v_cvt_pk_bf16_f32 v189, v158, v159
	v_cvt_pk_bf16_f32 v190, v160, v161
	v_cvt_pk_bf16_f32 v191, v162, v163
	v_cvt_pk_bf16_f32 v192, v164, v165
	v_cvt_pk_bf16_f32 v193, v166, v167
	v_cvt_pk_bf16_f32 v194, v168, v169
	v_cvt_pk_bf16_f32 v195, v170, v171
	v_lshl_add_u64 v[210:211], v[196:197], 1, s[10:11]
	global_store_dwordx4 v[210:211], v[188:191], off
	global_store_dwordx4 v[210:211], v[192:195], off offset:256
	v_mul_f32_e32 v157, v157, v157
	v_mul_f32_e32 v159, v159, v159
	v_mul_f32_e32 v161, v161, v161
	v_mul_f32_e32 v163, v163, v163
	v_mul_f32_e32 v165, v165, v165
	v_mul_f32_e32 v167, v167, v167
	v_mul_f32_e32 v169, v169, v169
	v_mul_f32_e32 v171, v171, v171
	v_fmac_f32_e32 v157, v156, v156
	v_fmac_f32_e32 v159, v158, v158
	v_fmac_f32_e32 v161, v160, v160
	v_fmac_f32_e32 v163, v162, v162
	v_fmac_f32_e32 v165, v164, v164
	v_fmac_f32_e32 v167, v166, v166
	v_fmac_f32_e32 v169, v168, v168
	v_fmac_f32_e32 v171, v170, v170
	v_add_f32_e32 v156, v157, v159
	v_add_f32_e32 v158, v161, v163
	v_add_f32_e32 v164, v165, v167
	v_add_f32_e32 v166, v169, v171
	v_add_f32_e32 v156, v156, v158
	v_add_f32_e32 v164, v164, v166
	v_add_f32_e32 v212, v156, v164
	v_mov_b32_e32 v213, v212
	s_nop 1
	v_permlane16_swap_b32_e32 v212, v213
	v_add_f32_e32 v212, v212, v213
	v_mov_b32_e32 v213, v212
	s_nop 1
	v_permlane32_swap_b32_e32 v212, v213
	s_and_saveexec_b64 s[28:29], s[2:3]
	v_lshlrev_b64 v[214:215], 6, v[204:205]
	v_lshl_add_u64 v[214:215], s[12:13], 0, v[214:215]
	v_lshl_add_u64 v[214:215], s[26:27], 2, v[214:215]
	v_lshl_add_u64 v[214:215], v[214:215], 0, s[6:7]
	v_add_f32_e32 v212, v212, v213
	global_store_dword v[214:215], v212, off
	s_or_b64 exec, exec, s[28:29]
	v_add_u32_e32 v204, 0xa0, v148
	v_ashrrev_i32_e32 v205, 31, v204
	v_lshlrev_b64 v[196:197], 10, v[204:205]
	v_lshl_add_u64 v[196:197], v[196:197], 0, v[146:147]
	v_lshl_add_u64 v[208:209], v[196:197], 1, s[10:11]
	global_load_dwordx4 v[172:175], v[208:209], off
	global_load_dwordx4 v[176:179], v[208:209], off offset:256
	s_waitcnt vmcnt(5)
	v_lshlrev_b32_e32 v156, 16, v180
	v_and_b32_e32 v157, 0xffff0000, v180
	v_lshlrev_b32_e32 v158, 16, v181
	v_and_b32_e32 v159, 0xffff0000, v181
	v_lshlrev_b32_e32 v160, 16, v182
	v_and_b32_e32 v161, 0xffff0000, v182
	v_lshlrev_b32_e32 v162, 16, v183
	v_and_b32_e32 v163, 0xffff0000, v183
	v_lshlrev_b32_e32 v164, 16, v184
	v_and_b32_e32 v165, 0xffff0000, v184
	v_lshlrev_b32_e32 v166, 16, v185
	v_and_b32_e32 v167, 0xffff0000, v185
	v_lshlrev_b32_e32 v168, 16, v186
	v_and_b32_e32 v169, 0xffff0000, v186
	v_lshlrev_b32_e32 v170, 16, v187
	v_and_b32_e32 v171, 0xffff0000, v187
	v_pk_add_f32 v[156:157], v[44:45], v[156:157]
	v_pk_add_f32 v[158:159], v[46:47], v[158:159]
	v_pk_add_f32 v[160:161], v[40:41], v[160:161]
	v_pk_add_f32 v[162:163], v[42:43], v[162:163]
	v_pk_add_f32 v[164:165], v[36:37], v[164:165]
	v_pk_add_f32 v[166:167], v[38:39], v[166:167]
	v_pk_add_f32 v[168:169], v[32:33], v[168:169]
	v_pk_add_f32 v[170:171], v[34:35], v[170:171]
	v_cvt_pk_bf16_f32 v188, v156, v157
	v_cvt_pk_bf16_f32 v189, v158, v159
	v_cvt_pk_bf16_f32 v190, v160, v161
	v_cvt_pk_bf16_f32 v191, v162, v163
	v_cvt_pk_bf16_f32 v192, v164, v165
	v_cvt_pk_bf16_f32 v193, v166, v167
	v_cvt_pk_bf16_f32 v194, v168, v169
	v_cvt_pk_bf16_f32 v195, v170, v171
	v_lshl_add_u64 v[210:211], v[198:199], 1, s[10:11]
	global_store_dwordx4 v[210:211], v[188:191], off
	global_store_dwordx4 v[210:211], v[192:195], off offset:256
	v_mul_f32_e32 v157, v157, v157
	v_mul_f32_e32 v159, v159, v159
	v_mul_f32_e32 v161, v161, v161
	v_mul_f32_e32 v163, v163, v163
	v_mul_f32_e32 v165, v165, v165
	v_mul_f32_e32 v167, v167, v167
	v_mul_f32_e32 v169, v169, v169
	v_mul_f32_e32 v171, v171, v171
	v_fmac_f32_e32 v157, v156, v156
	v_fmac_f32_e32 v159, v158, v158
	v_fmac_f32_e32 v161, v160, v160
	v_fmac_f32_e32 v163, v162, v162
	v_fmac_f32_e32 v165, v164, v164
	v_fmac_f32_e32 v167, v166, v166
	v_fmac_f32_e32 v169, v168, v168
	v_fmac_f32_e32 v171, v170, v170
	v_add_f32_e32 v156, v157, v159
	v_add_f32_e32 v158, v161, v163
	v_add_f32_e32 v164, v165, v167
	v_add_f32_e32 v166, v169, v171
	v_add_f32_e32 v156, v156, v158
	v_add_f32_e32 v164, v164, v166
	v_add_f32_e32 v212, v156, v164
	v_mov_b32_e32 v213, v212
	s_nop 1
	v_permlane16_swap_b32_e32 v212, v213
	v_add_f32_e32 v212, v212, v213
	v_mov_b32_e32 v213, v212
	s_nop 1
	v_permlane32_swap_b32_e32 v212, v213
	s_and_saveexec_b64 s[28:29], s[2:3]
	v_lshlrev_b64 v[214:215], 6, v[206:207]
	v_lshl_add_u64 v[214:215], s[12:13], 0, v[214:215]
	v_lshl_add_u64 v[214:215], s[26:27], 2, v[214:215]
	v_lshl_add_u64 v[214:215], v[214:215], 0, s[6:7]
	v_add_f32_e32 v212, v212, v213
	global_store_dword v[214:215], v212, off
	s_or_b64 exec, exec, s[28:29]
	v_add_u32_e32 v206, 0xb0, v148
	v_ashrrev_i32_e32 v207, 31, v206
	v_lshlrev_b64 v[198:199], 10, v[206:207]
	v_lshl_add_u64 v[198:199], v[198:199], 0, v[146:147]
	v_lshl_add_u64 v[208:209], v[198:199], 1, s[10:11]
	global_load_dwordx4 v[180:183], v[208:209], off
	global_load_dwordx4 v[184:187], v[208:209], off offset:256
	s_waitcnt vmcnt(5)
	v_lshlrev_b32_e32 v156, 16, v172
	v_and_b32_e32 v157, 0xffff0000, v172
	v_lshlrev_b32_e32 v158, 16, v173
	v_and_b32_e32 v159, 0xffff0000, v173
	v_lshlrev_b32_e32 v160, 16, v174
	v_and_b32_e32 v161, 0xffff0000, v174
	v_lshlrev_b32_e32 v162, 16, v175
	v_and_b32_e32 v163, 0xffff0000, v175
	v_lshlrev_b32_e32 v164, 16, v176
	v_and_b32_e32 v165, 0xffff0000, v176
	v_lshlrev_b32_e32 v166, 16, v177
	v_and_b32_e32 v167, 0xffff0000, v177
	v_lshlrev_b32_e32 v168, 16, v178
	v_and_b32_e32 v169, 0xffff0000, v178
	v_lshlrev_b32_e32 v170, 16, v179
	v_and_b32_e32 v171, 0xffff0000, v179
	v_pk_add_f32 v[156:157], v[28:29], v[156:157]
	v_pk_add_f32 v[158:159], v[30:31], v[158:159]
	v_pk_add_f32 v[160:161], v[24:25], v[160:161]
	v_pk_add_f32 v[162:163], v[26:27], v[162:163]
	v_pk_add_f32 v[164:165], v[20:21], v[164:165]
	v_pk_add_f32 v[166:167], v[22:23], v[166:167]
	v_pk_add_f32 v[168:169], v[16:17], v[168:169]
	v_pk_add_f32 v[170:171], v[18:19], v[170:171]
	v_cvt_pk_bf16_f32 v188, v156, v157
	v_cvt_pk_bf16_f32 v189, v158, v159
	v_cvt_pk_bf16_f32 v190, v160, v161
	v_cvt_pk_bf16_f32 v191, v162, v163
	v_cvt_pk_bf16_f32 v192, v164, v165
	v_cvt_pk_bf16_f32 v193, v166, v167
	v_cvt_pk_bf16_f32 v194, v168, v169
	v_cvt_pk_bf16_f32 v195, v170, v171
	v_lshl_add_u64 v[210:211], v[196:197], 1, s[10:11]
	global_store_dwordx4 v[210:211], v[188:191], off
	global_store_dwordx4 v[210:211], v[192:195], off offset:256
	v_mul_f32_e32 v157, v157, v157
	v_mul_f32_e32 v159, v159, v159
	v_mul_f32_e32 v161, v161, v161
	v_mul_f32_e32 v163, v163, v163
	v_mul_f32_e32 v165, v165, v165
	v_mul_f32_e32 v167, v167, v167
	v_mul_f32_e32 v169, v169, v169
	v_mul_f32_e32 v171, v171, v171
	v_fmac_f32_e32 v157, v156, v156
	v_fmac_f32_e32 v159, v158, v158
	v_fmac_f32_e32 v161, v160, v160
	v_fmac_f32_e32 v163, v162, v162
	v_fmac_f32_e32 v165, v164, v164
	v_fmac_f32_e32 v167, v166, v166
	v_fmac_f32_e32 v169, v168, v168
	v_fmac_f32_e32 v171, v170, v170
	v_add_f32_e32 v156, v157, v159
	v_add_f32_e32 v158, v161, v163
	v_add_f32_e32 v164, v165, v167
	v_add_f32_e32 v166, v169, v171
	v_add_f32_e32 v156, v156, v158
	v_add_f32_e32 v164, v164, v166
	v_add_f32_e32 v212, v156, v164
	v_mov_b32_e32 v213, v212
	s_nop 1
	v_permlane16_swap_b32_e32 v212, v213
	v_add_f32_e32 v212, v212, v213
	v_mov_b32_e32 v213, v212
	s_nop 1
	v_permlane32_swap_b32_e32 v212, v213
	s_and_saveexec_b64 s[28:29], s[2:3]
	v_lshlrev_b64 v[214:215], 6, v[204:205]
	v_lshl_add_u64 v[214:215], s[12:13], 0, v[214:215]
	v_lshl_add_u64 v[214:215], s[26:27], 2, v[214:215]
	v_lshl_add_u64 v[214:215], v[214:215], 0, s[6:7]
	v_add_f32_e32 v212, v212, v213
	global_store_dword v[214:215], v212, off
	s_or_b64 exec, exec, s[28:29]
	s_waitcnt vmcnt(3)
	v_lshlrev_b32_e32 v156, 16, v180
	v_and_b32_e32 v157, 0xffff0000, v180
	v_lshlrev_b32_e32 v158, 16, v181
	v_and_b32_e32 v159, 0xffff0000, v181
	v_lshlrev_b32_e32 v160, 16, v182
	v_and_b32_e32 v161, 0xffff0000, v182
	v_lshlrev_b32_e32 v162, 16, v183
	v_and_b32_e32 v163, 0xffff0000, v183
	v_lshlrev_b32_e32 v164, 16, v184
	v_and_b32_e32 v165, 0xffff0000, v184
	v_lshlrev_b32_e32 v166, 16, v185
	v_and_b32_e32 v167, 0xffff0000, v185
	v_lshlrev_b32_e32 v168, 16, v186
	v_and_b32_e32 v169, 0xffff0000, v186
	v_lshlrev_b32_e32 v170, 16, v187
	v_and_b32_e32 v171, 0xffff0000, v187
	v_pk_add_f32 v[156:157], v[12:13], v[156:157]
	v_pk_add_f32 v[158:159], v[14:15], v[158:159]
	v_pk_add_f32 v[160:161], v[8:9], v[160:161]
	v_pk_add_f32 v[162:163], v[10:11], v[162:163]
	v_pk_add_f32 v[164:165], v[4:5], v[164:165]
	v_pk_add_f32 v[166:167], v[6:7], v[166:167]
	v_pk_add_f32 v[168:169], v[0:1], v[168:169]
	v_pk_add_f32 v[170:171], v[2:3], v[170:171]
	v_cvt_pk_bf16_f32 v188, v156, v157
	v_cvt_pk_bf16_f32 v189, v158, v159
	v_cvt_pk_bf16_f32 v190, v160, v161
	v_cvt_pk_bf16_f32 v191, v162, v163
	v_cvt_pk_bf16_f32 v192, v164, v165
	v_cvt_pk_bf16_f32 v193, v166, v167
	v_cvt_pk_bf16_f32 v194, v168, v169
	v_cvt_pk_bf16_f32 v195, v170, v171
	v_lshl_add_u64 v[210:211], v[198:199], 1, s[10:11]
	global_store_dwordx4 v[210:211], v[188:191], off
	global_store_dwordx4 v[210:211], v[192:195], off offset:256
	v_mul_f32_e32 v157, v157, v157
	v_mul_f32_e32 v159, v159, v159
	v_mul_f32_e32 v161, v161, v161
	v_mul_f32_e32 v163, v163, v163
	v_mul_f32_e32 v165, v165, v165
	v_mul_f32_e32 v167, v167, v167
	v_mul_f32_e32 v169, v169, v169
	v_mul_f32_e32 v171, v171, v171
	v_fmac_f32_e32 v157, v156, v156
	v_fmac_f32_e32 v159, v158, v158
	v_fmac_f32_e32 v161, v160, v160
	v_fmac_f32_e32 v163, v162, v162
	v_fmac_f32_e32 v165, v164, v164
	v_fmac_f32_e32 v167, v166, v166
	v_fmac_f32_e32 v169, v168, v168
	v_fmac_f32_e32 v171, v170, v170
	v_add_f32_e32 v156, v157, v159
	v_add_f32_e32 v158, v161, v163
	v_add_f32_e32 v164, v165, v167
	v_add_f32_e32 v166, v169, v171
	v_add_f32_e32 v156, v156, v158
	v_add_f32_e32 v164, v164, v166
	v_add_f32_e32 v212, v156, v164
	v_mov_b32_e32 v213, v212
	s_nop 1
	v_permlane16_swap_b32_e32 v212, v213
	v_add_f32_e32 v212, v212, v213
	v_mov_b32_e32 v213, v212
	s_nop 1
	v_permlane32_swap_b32_e32 v212, v213
	s_and_saveexec_b64 s[28:29], s[2:3]
	v_lshlrev_b64 v[214:215], 6, v[206:207]
	v_lshl_add_u64 v[214:215], s[12:13], 0, v[214:215]
	v_lshl_add_u64 v[214:215], s[26:27], 2, v[214:215]
	v_lshl_add_u64 v[214:215], v[214:215], 0, s[6:7]
	v_add_f32_e32 v212, v212, v213
	global_store_dword v[214:215], v212, off
	s_or_b64 exec, exec, s[28:29]

.LBB0_2737:
	v_lshl_add_u32 v148, s52, 8, v137
	s_lshl_b32 s24, s8, 8
	s_ashr_i32 s25, s24, 31
	v_ashrrev_i32_e32 v149, 31, v148
	v_mov_b32_e32 v147, s25
	v_or_b32_e32 v146, s24, v136
	s_lshl_b32 s24, s8, 2
	s_ashr_i32 s25, s24, 31
	s_lshl_b32 s8, s43, 2
	v_mov_b32_e32 v204, v148
	v_ashrrev_i32_e32 v205, 31, v204
	v_lshlrev_b64 v[196:197], 10, v[204:205]
	v_lshl_add_u64 v[196:197], v[196:197], 0, v[146:147]
	v_lshl_add_u64 v[208:209], v[196:197], 1, s[12:13]
	global_load_dwordx4 v[172:175], v[208:209], off
	global_load_dwordx4 v[176:179], v[208:209], off offset:256
	v_or_b32_e32 v206, 16, v148
	v_ashrrev_i32_e32 v207, 31, v206
	v_lshlrev_b64 v[198:199], 10, v[206:207]
	v_lshl_add_u64 v[198:199], v[198:199], 0, v[146:147]
	v_lshl_add_u64 v[208:209], v[198:199], 1, s[12:13]
	global_load_dwordx4 v[180:183], v[208:209], off
	global_load_dwordx4 v[184:187], v[208:209], off offset:256
	s_waitcnt vmcnt(2)
	v_lshlrev_b32_e32 v156, 16, v172
	v_and_b32_e32 v157, 0xffff0000, v172
	v_lshlrev_b32_e32 v158, 16, v173
	v_and_b32_e32 v159, 0xffff0000, v173
	v_lshlrev_b32_e32 v160, 16, v174
	v_and_b32_e32 v161, 0xffff0000, v174
	v_lshlrev_b32_e32 v162, 16, v175
	v_and_b32_e32 v163, 0xffff0000, v175
	v_lshlrev_b32_e32 v164, 16, v176
	v_and_b32_e32 v165, 0xffff0000, v176
	v_lshlrev_b32_e32 v166, 16, v177
	v_and_b32_e32 v167, 0xffff0000, v177
	v_lshlrev_b32_e32 v168, 16, v178
	v_and_b32_e32 v169, 0xffff0000, v178
	v_lshlrev_b32_e32 v170, 16, v179
	v_and_b32_e32 v171, 0xffff0000, v179
	v_pk_add_f32 v[156:157], v[124:125], v[156:157]
	v_pk_add_f32 v[158:159], v[126:127], v[158:159]
	v_pk_add_f32 v[160:161], v[120:121], v[160:161]
	v_pk_add_f32 v[162:163], v[122:123], v[162:163]
	v_pk_add_f32 v[164:165], v[116:117], v[164:165]
	v_pk_add_f32 v[166:167], v[118:119], v[166:167]
	v_pk_add_f32 v[168:169], v[112:113], v[168:169]
	v_pk_add_f32 v[170:171], v[114:115], v[170:171]
	v_cvt_pk_bf16_f32 v188, v156, v157
	v_cvt_pk_bf16_f32 v189, v158, v159
	v_cvt_pk_bf16_f32 v190, v160, v161
	v_cvt_pk_bf16_f32 v191, v162, v163
	v_cvt_pk_bf16_f32 v192, v164, v165
	v_cvt_pk_bf16_f32 v193, v166, v167
	v_cvt_pk_bf16_f32 v194, v168, v169
	v_cvt_pk_bf16_f32 v195, v170, v171
	v_lshl_add_u64 v[210:211], v[196:197], 1, s[14:15]
	global_store_dwordx4 v[210:211], v[188:191], off
	global_store_dwordx4 v[210:211], v[192:195], off offset:256
	v_mul_f32_e32 v157, v157, v157
	v_mul_f32_e32 v159, v159, v159
	v_mul_f32_e32 v161, v161, v161
	v_mul_f32_e32 v163, v163, v163
	v_mul_f32_e32 v165, v165, v165
	v_mul_f32_e32 v167, v167, v167
	v_mul_f32_e32 v169, v169, v169
	v_mul_f32_e32 v171, v171, v171
	v_fmac_f32_e32 v157, v156, v156
	v_fmac_f32_e32 v159, v158, v158
	v_fmac_f32_e32 v161, v160, v160
	v_fmac_f32_e32 v163, v162, v162
	v_fmac_f32_e32 v165, v164, v164
	v_fmac_f32_e32 v167, v166, v166
	v_fmac_f32_e32 v169, v168, v168
	v_fmac_f32_e32 v171, v170, v170
	v_add_f32_e32 v156, v157, v159
	v_add_f32_e32 v158, v161, v163
	v_add_f32_e32 v164, v165, v167
	v_add_f32_e32 v166, v169, v171
	v_add_f32_e32 v156, v156, v158
	v_add_f32_e32 v164, v164, v166
	v_add_f32_e32 v212, v156, v164
	v_mov_b32_e32 v213, v212
	s_nop 1
	v_permlane16_swap_b32_e32 v212, v213
	v_add_f32_e32 v212, v212, v213
	v_mov_b32_e32 v213, v212
	s_nop 1
	v_permlane32_swap_b32_e32 v212, v213
	s_and_saveexec_b64 s[26:27], s[2:3]
	v_lshlrev_b64 v[214:215], 6, v[204:205]
	v_lshl_add_u64 v[214:215], s[16:17], 0, v[214:215]
	v_lshl_add_u64 v[214:215], s[24:25], 2, v[214:215]
	v_lshl_add_u64 v[214:215], v[214:215], 0, s[8:9]
	v_add_f32_e32 v212, v212, v213
	global_store_dword v[214:215], v212, off
	s_or_b64 exec, exec, s[26:27]
	v_or_b32_e32 v204, 32, v148
	v_ashrrev_i32_e32 v205, 31, v204
	v_lshlrev_b64 v[196:197], 10, v[204:205]
	v_lshl_add_u64 v[196:197], v[196:197], 0, v[146:147]
	v_lshl_add_u64 v[208:209], v[196:197], 1, s[12:13]
	global_load_dwordx4 v[172:175], v[208:209], off
	global_load_dwordx4 v[176:179], v[208:209], off offset:256
	s_waitcnt vmcnt(5)
	v_lshlrev_b32_e32 v156, 16, v180
	v_and_b32_e32 v157, 0xffff0000, v180
	v_lshlrev_b32_e32 v158, 16, v181
	v_and_b32_e32 v159, 0xffff0000, v181
	v_lshlrev_b32_e32 v160, 16, v182
	v_and_b32_e32 v161, 0xffff0000, v182
	v_lshlrev_b32_e32 v162, 16, v183
	v_and_b32_e32 v163, 0xffff0000, v183
	v_lshlrev_b32_e32 v164, 16, v184
	v_and_b32_e32 v165, 0xffff0000, v184
	v_lshlrev_b32_e32 v166, 16, v185
	v_and_b32_e32 v167, 0xffff0000, v185
	v_lshlrev_b32_e32 v168, 16, v186
	v_and_b32_e32 v169, 0xffff0000, v186
	v_lshlrev_b32_e32 v170, 16, v187
	v_and_b32_e32 v171, 0xffff0000, v187
	v_pk_add_f32 v[156:157], v[108:109], v[156:157]
	v_pk_add_f32 v[158:159], v[110:111], v[158:159]
	v_pk_add_f32 v[160:161], v[104:105], v[160:161]
	v_pk_add_f32 v[162:163], v[106:107], v[162:163]
	v_pk_add_f32 v[164:165], v[100:101], v[164:165]
	v_pk_add_f32 v[166:167], v[102:103], v[166:167]
	v_pk_add_f32 v[168:169], v[96:97], v[168:169]
	v_pk_add_f32 v[170:171], v[98:99], v[170:171]
	v_cvt_pk_bf16_f32 v188, v156, v157
	v_cvt_pk_bf16_f32 v189, v158, v159
	v_cvt_pk_bf16_f32 v190, v160, v161
	v_cvt_pk_bf16_f32 v191, v162, v163
	v_cvt_pk_bf16_f32 v192, v164, v165
	v_cvt_pk_bf16_f32 v193, v166, v167
	v_cvt_pk_bf16_f32 v194, v168, v169
	v_cvt_pk_bf16_f32 v195, v170, v171
	v_lshl_add_u64 v[210:211], v[198:199], 1, s[14:15]
	global_store_dwordx4 v[210:211], v[188:191], off
	global_store_dwordx4 v[210:211], v[192:195], off offset:256
	v_mul_f32_e32 v157, v157, v157
	v_mul_f32_e32 v159, v159, v159
	v_mul_f32_e32 v161, v161, v161
	v_mul_f32_e32 v163, v163, v163
	v_mul_f32_e32 v165, v165, v165
	v_mul_f32_e32 v167, v167, v167
	v_mul_f32_e32 v169, v169, v169
	v_mul_f32_e32 v171, v171, v171
	v_fmac_f32_e32 v157, v156, v156
	v_fmac_f32_e32 v159, v158, v158
	v_fmac_f32_e32 v161, v160, v160
	v_fmac_f32_e32 v163, v162, v162
	v_fmac_f32_e32 v165, v164, v164
	v_fmac_f32_e32 v167, v166, v166
	v_fmac_f32_e32 v169, v168, v168
	v_fmac_f32_e32 v171, v170, v170
	v_add_f32_e32 v156, v157, v159
	v_add_f32_e32 v158, v161, v163
	v_add_f32_e32 v164, v165, v167
	v_add_f32_e32 v166, v169, v171
	v_add_f32_e32 v156, v156, v158
	v_add_f32_e32 v164, v164, v166
	v_add_f32_e32 v212, v156, v164
	v_mov_b32_e32 v213, v212
	s_nop 1
	v_permlane16_swap_b32_e32 v212, v213
	v_add_f32_e32 v212, v212, v213
	v_mov_b32_e32 v213, v212
	s_nop 1
	v_permlane32_swap_b32_e32 v212, v213
	s_and_saveexec_b64 s[26:27], s[2:3]
	v_lshlrev_b64 v[214:215], 6, v[206:207]
	v_lshl_add_u64 v[214:215], s[16:17], 0, v[214:215]
	v_lshl_add_u64 v[214:215], s[24:25], 2, v[214:215]
	v_lshl_add_u64 v[214:215], v[214:215], 0, s[8:9]
	v_add_f32_e32 v212, v212, v213
	global_store_dword v[214:215], v212, off
	s_or_b64 exec, exec, s[26:27]
	v_or_b32_e32 v206, 48, v148
	v_ashrrev_i32_e32 v207, 31, v206
	v_lshlrev_b64 v[198:199], 10, v[206:207]
	v_lshl_add_u64 v[198:199], v[198:199], 0, v[146:147]
	v_lshl_add_u64 v[208:209], v[198:199], 1, s[12:13]
	global_load_dwordx4 v[180:183], v[208:209], off
	global_load_dwordx4 v[184:187], v[208:209], off offset:256
	s_waitcnt vmcnt(5)
	v_lshlrev_b32_e32 v156, 16, v172
	v_and_b32_e32 v157, 0xffff0000, v172
	v_lshlrev_b32_e32 v158, 16, v173
	v_and_b32_e32 v159, 0xffff0000, v173
	v_lshlrev_b32_e32 v160, 16, v174
	v_and_b32_e32 v161, 0xffff0000, v174
	v_lshlrev_b32_e32 v162, 16, v175
	v_and_b32_e32 v163, 0xffff0000, v175
	v_lshlrev_b32_e32 v164, 16, v176
	v_and_b32_e32 v165, 0xffff0000, v176
	v_lshlrev_b32_e32 v166, 16, v177
	v_and_b32_e32 v167, 0xffff0000, v177
	v_lshlrev_b32_e32 v168, 16, v178
	v_and_b32_e32 v169, 0xffff0000, v178
	v_lshlrev_b32_e32 v170, 16, v179
	v_and_b32_e32 v171, 0xffff0000, v179
	v_pk_add_f32 v[156:157], v[92:93], v[156:157]
	v_pk_add_f32 v[158:159], v[94:95], v[158:159]
	v_pk_add_f32 v[160:161], v[88:89], v[160:161]
	v_pk_add_f32 v[162:163], v[90:91], v[162:163]
	v_pk_add_f32 v[164:165], v[84:85], v[164:165]
	v_pk_add_f32 v[166:167], v[86:87], v[166:167]
	v_pk_add_f32 v[168:169], v[80:81], v[168:169]
	v_pk_add_f32 v[170:171], v[82:83], v[170:171]
	v_cvt_pk_bf16_f32 v188, v156, v157
	v_cvt_pk_bf16_f32 v189, v158, v159
	v_cvt_pk_bf16_f32 v190, v160, v161
	v_cvt_pk_bf16_f32 v191, v162, v163
	v_cvt_pk_bf16_f32 v192, v164, v165
	v_cvt_pk_bf16_f32 v193, v166, v167
	v_cvt_pk_bf16_f32 v194, v168, v169
	v_cvt_pk_bf16_f32 v195, v170, v171
	v_lshl_add_u64 v[210:211], v[196:197], 1, s[14:15]
	global_store_dwordx4 v[210:211], v[188:191], off
	global_store_dwordx4 v[210:211], v[192:195], off offset:256
	v_mul_f32_e32 v157, v157, v157
	v_mul_f32_e32 v159, v159, v159
	v_mul_f32_e32 v161, v161, v161
	v_mul_f32_e32 v163, v163, v163
	v_mul_f32_e32 v165, v165, v165
	v_mul_f32_e32 v167, v167, v167
	v_mul_f32_e32 v169, v169, v169
	v_mul_f32_e32 v171, v171, v171
	v_fmac_f32_e32 v157, v156, v156
	v_fmac_f32_e32 v159, v158, v158
	v_fmac_f32_e32 v161, v160, v160
	v_fmac_f32_e32 v163, v162, v162
	v_fmac_f32_e32 v165, v164, v164
	v_fmac_f32_e32 v167, v166, v166
	v_fmac_f32_e32 v169, v168, v168
	v_fmac_f32_e32 v171, v170, v170
	v_add_f32_e32 v156, v157, v159
	v_add_f32_e32 v158, v161, v163
	v_add_f32_e32 v164, v165, v167
	v_add_f32_e32 v166, v169, v171
	v_add_f32_e32 v156, v156, v158
	v_add_f32_e32 v164, v164, v166
	v_add_f32_e32 v212, v156, v164
	v_mov_b32_e32 v213, v212
	s_nop 1
	v_permlane16_swap_b32_e32 v212, v213
	v_add_f32_e32 v212, v212, v213
	v_mov_b32_e32 v213, v212
	s_nop 1
	v_permlane32_swap_b32_e32 v212, v213
	s_and_saveexec_b64 s[26:27], s[2:3]
	v_lshlrev_b64 v[214:215], 6, v[204:205]
	v_lshl_add_u64 v[214:215], s[16:17], 0, v[214:215]
	v_lshl_add_u64 v[214:215], s[24:25], 2, v[214:215]
	v_lshl_add_u64 v[214:215], v[214:215], 0, s[8:9]
	v_add_f32_e32 v212, v212, v213
	global_store_dword v[214:215], v212, off
	s_or_b64 exec, exec, s[26:27]
	v_add_u32_e32 v204, 0x80, v148
	v_ashrrev_i32_e32 v205, 31, v204
	v_lshlrev_b64 v[196:197], 10, v[204:205]
	v_lshl_add_u64 v[196:197], v[196:197], 0, v[146:147]
	v_lshl_add_u64 v[208:209], v[196:197], 1, s[12:13]
	global_load_dwordx4 v[172:175], v[208:209], off
	global_load_dwordx4 v[176:179], v[208:209], off offset:256
	s_waitcnt vmcnt(5)
	v_lshlrev_b32_e32 v156, 16, v180
	v_and_b32_e32 v157, 0xffff0000, v180
	v_lshlrev_b32_e32 v158, 16, v181
	v_and_b32_e32 v159, 0xffff0000, v181
	v_lshlrev_b32_e32 v160, 16, v182
	v_and_b32_e32 v161, 0xffff0000, v182
	v_lshlrev_b32_e32 v162, 16, v183
	v_and_b32_e32 v163, 0xffff0000, v183
	v_lshlrev_b32_e32 v164, 16, v184
	v_and_b32_e32 v165, 0xffff0000, v184
	v_lshlrev_b32_e32 v166, 16, v185
	v_and_b32_e32 v167, 0xffff0000, v185
	v_lshlrev_b32_e32 v168, 16, v186
	v_and_b32_e32 v169, 0xffff0000, v186
	v_lshlrev_b32_e32 v170, 16, v187
	v_and_b32_e32 v171, 0xffff0000, v187
	v_pk_add_f32 v[156:157], v[76:77], v[156:157]
	v_pk_add_f32 v[158:159], v[78:79], v[158:159]
	v_pk_add_f32 v[160:161], v[72:73], v[160:161]
	v_pk_add_f32 v[162:163], v[74:75], v[162:163]
	v_pk_add_f32 v[164:165], v[68:69], v[164:165]
	v_pk_add_f32 v[166:167], v[70:71], v[166:167]
	v_pk_add_f32 v[168:169], v[64:65], v[168:169]
	v_pk_add_f32 v[170:171], v[66:67], v[170:171]
	v_cvt_pk_bf16_f32 v188, v156, v157
	v_cvt_pk_bf16_f32 v189, v158, v159
	v_cvt_pk_bf16_f32 v190, v160, v161
	v_cvt_pk_bf16_f32 v191, v162, v163
	v_cvt_pk_bf16_f32 v192, v164, v165
	v_cvt_pk_bf16_f32 v193, v166, v167
	v_cvt_pk_bf16_f32 v194, v168, v169
	v_cvt_pk_bf16_f32 v195, v170, v171
	v_lshl_add_u64 v[210:211], v[198:199], 1, s[14:15]
	global_store_dwordx4 v[210:211], v[188:191], off
	global_store_dwordx4 v[210:211], v[192:195], off offset:256
	v_mul_f32_e32 v157, v157, v157
	v_mul_f32_e32 v159, v159, v159
	v_mul_f32_e32 v161, v161, v161
	v_mul_f32_e32 v163, v163, v163
	v_mul_f32_e32 v165, v165, v165
	v_mul_f32_e32 v167, v167, v167
	v_mul_f32_e32 v169, v169, v169
	v_mul_f32_e32 v171, v171, v171
	v_fmac_f32_e32 v157, v156, v156
	v_fmac_f32_e32 v159, v158, v158
	v_fmac_f32_e32 v161, v160, v160
	v_fmac_f32_e32 v163, v162, v162
	v_fmac_f32_e32 v165, v164, v164
	v_fmac_f32_e32 v167, v166, v166
	v_fmac_f32_e32 v169, v168, v168
	v_fmac_f32_e32 v171, v170, v170
	v_add_f32_e32 v156, v157, v159
	v_add_f32_e32 v158, v161, v163
	v_add_f32_e32 v164, v165, v167
	v_add_f32_e32 v166, v169, v171
	v_add_f32_e32 v156, v156, v158
	v_add_f32_e32 v164, v164, v166
	v_add_f32_e32 v212, v156, v164
	v_mov_b32_e32 v213, v212
	s_nop 1
	v_permlane16_swap_b32_e32 v212, v213
	v_add_f32_e32 v212, v212, v213
	v_mov_b32_e32 v213, v212
	s_nop 1
	v_permlane32_swap_b32_e32 v212, v213
	s_and_saveexec_b64 s[26:27], s[2:3]
	v_lshlrev_b64 v[214:215], 6, v[206:207]
	v_lshl_add_u64 v[214:215], s[16:17], 0, v[214:215]
	v_lshl_add_u64 v[214:215], s[24:25], 2, v[214:215]
	v_lshl_add_u64 v[214:215], v[214:215], 0, s[8:9]
	v_add_f32_e32 v212, v212, v213
	global_store_dword v[214:215], v212, off
	s_or_b64 exec, exec, s[26:27]
	v_add_u32_e32 v206, 0x90, v148
	v_ashrrev_i32_e32 v207, 31, v206
	v_lshlrev_b64 v[198:199], 10, v[206:207]
	v_lshl_add_u64 v[198:199], v[198:199], 0, v[146:147]
	v_lshl_add_u64 v[208:209], v[198:199], 1, s[12:13]
	global_load_dwordx4 v[180:183], v[208:209], off
	global_load_dwordx4 v[184:187], v[208:209], off offset:256
	s_waitcnt vmcnt(5)
	v_lshlrev_b32_e32 v156, 16, v172
	v_and_b32_e32 v157, 0xffff0000, v172
	v_lshlrev_b32_e32 v158, 16, v173
	v_and_b32_e32 v159, 0xffff0000, v173
	v_lshlrev_b32_e32 v160, 16, v174
	v_and_b32_e32 v161, 0xffff0000, v174
	v_lshlrev_b32_e32 v162, 16, v175
	v_and_b32_e32 v163, 0xffff0000, v175
	v_lshlrev_b32_e32 v164, 16, v176
	v_and_b32_e32 v165, 0xffff0000, v176
	v_lshlrev_b32_e32 v166, 16, v177
	v_and_b32_e32 v167, 0xffff0000, v177
	v_lshlrev_b32_e32 v168, 16, v178
	v_and_b32_e32 v169, 0xffff0000, v178
	v_lshlrev_b32_e32 v170, 16, v179
	v_and_b32_e32 v171, 0xffff0000, v179
	v_pk_add_f32 v[156:157], v[60:61], v[156:157]
	v_pk_add_f32 v[158:159], v[62:63], v[158:159]
	v_pk_add_f32 v[160:161], v[56:57], v[160:161]
	v_pk_add_f32 v[162:163], v[58:59], v[162:163]
	v_pk_add_f32 v[164:165], v[52:53], v[164:165]
	v_pk_add_f32 v[166:167], v[54:55], v[166:167]
	v_pk_add_f32 v[168:169], v[48:49], v[168:169]
	v_pk_add_f32 v[170:171], v[50:51], v[170:171]
	v_cvt_pk_bf16_f32 v188, v156, v157
	v_cvt_pk_bf16_f32 v189, v158, v159
	v_cvt_pk_bf16_f32 v190, v160, v161
	v_cvt_pk_bf16_f32 v191, v162, v163
	v_cvt_pk_bf16_f32 v192, v164, v165
	v_cvt_pk_bf16_f32 v193, v166, v167
	v_cvt_pk_bf16_f32 v194, v168, v169
	v_cvt_pk_bf16_f32 v195, v170, v171
	v_lshl_add_u64 v[210:211], v[196:197], 1, s[14:15]
	global_store_dwordx4 v[210:211], v[188:191], off
	global_store_dwordx4 v[210:211], v[192:195], off offset:256
	v_mul_f32_e32 v157, v157, v157
	v_mul_f32_e32 v159, v159, v159
	v_mul_f32_e32 v161, v161, v161
	v_mul_f32_e32 v163, v163, v163
	v_mul_f32_e32 v165, v165, v165
	v_mul_f32_e32 v167, v167, v167
	v_mul_f32_e32 v169, v169, v169
	v_mul_f32_e32 v171, v171, v171
	v_fmac_f32_e32 v157, v156, v156
	v_fmac_f32_e32 v159, v158, v158
	v_fmac_f32_e32 v161, v160, v160
	v_fmac_f32_e32 v163, v162, v162
	v_fmac_f32_e32 v165, v164, v164
	v_fmac_f32_e32 v167, v166, v166
	v_fmac_f32_e32 v169, v168, v168
	v_fmac_f32_e32 v171, v170, v170
	v_add_f32_e32 v156, v157, v159
	v_add_f32_e32 v158, v161, v163
	v_add_f32_e32 v164, v165, v167
	v_add_f32_e32 v166, v169, v171
	v_add_f32_e32 v156, v156, v158
	v_add_f32_e32 v164, v164, v166
	v_add_f32_e32 v212, v156, v164
	v_mov_b32_e32 v213, v212
	s_nop 1
	v_permlane16_swap_b32_e32 v212, v213
	v_add_f32_e32 v212, v212, v213
	v_mov_b32_e32 v213, v212
	s_nop 1
	v_permlane32_swap_b32_e32 v212, v213
	s_and_saveexec_b64 s[26:27], s[2:3]
	v_lshlrev_b64 v[214:215], 6, v[204:205]
	v_lshl_add_u64 v[214:215], s[16:17], 0, v[214:215]
	v_lshl_add_u64 v[214:215], s[24:25], 2, v[214:215]
	v_lshl_add_u64 v[214:215], v[214:215], 0, s[8:9]
	v_add_f32_e32 v212, v212, v213
	global_store_dword v[214:215], v212, off
	s_or_b64 exec, exec, s[26:27]
	v_add_u32_e32 v204, 0xa0, v148
	v_ashrrev_i32_e32 v205, 31, v204
	v_lshlrev_b64 v[196:197], 10, v[204:205]
	v_lshl_add_u64 v[196:197], v[196:197], 0, v[146:147]
	v_lshl_add_u64 v[208:209], v[196:197], 1, s[12:13]
	global_load_dwordx4 v[172:175], v[208:209], off
	global_load_dwordx4 v[176:179], v[208:209], off offset:256
	s_waitcnt vmcnt(5)
	v_lshlrev_b32_e32 v156, 16, v180
	v_and_b32_e32 v157, 0xffff0000, v180
	v_lshlrev_b32_e32 v158, 16, v181
	v_and_b32_e32 v159, 0xffff0000, v181
	v_lshlrev_b32_e32 v160, 16, v182
	v_and_b32_e32 v161, 0xffff0000, v182
	v_lshlrev_b32_e32 v162, 16, v183
	v_and_b32_e32 v163, 0xffff0000, v183
	v_lshlrev_b32_e32 v164, 16, v184
	v_and_b32_e32 v165, 0xffff0000, v184
	v_lshlrev_b32_e32 v166, 16, v185
	v_and_b32_e32 v167, 0xffff0000, v185
	v_lshlrev_b32_e32 v168, 16, v186
	v_and_b32_e32 v169, 0xffff0000, v186
	v_lshlrev_b32_e32 v170, 16, v187
	v_and_b32_e32 v171, 0xffff0000, v187
	v_pk_add_f32 v[156:157], v[44:45], v[156:157]
	v_pk_add_f32 v[158:159], v[46:47], v[158:159]
	v_pk_add_f32 v[160:161], v[40:41], v[160:161]
	v_pk_add_f32 v[162:163], v[42:43], v[162:163]
	v_pk_add_f32 v[164:165], v[36:37], v[164:165]
	v_pk_add_f32 v[166:167], v[38:39], v[166:167]
	v_pk_add_f32 v[168:169], v[32:33], v[168:169]
	v_pk_add_f32 v[170:171], v[34:35], v[170:171]
	v_cvt_pk_bf16_f32 v188, v156, v157
	v_cvt_pk_bf16_f32 v189, v158, v159
	v_cvt_pk_bf16_f32 v190, v160, v161
	v_cvt_pk_bf16_f32 v191, v162, v163
	v_cvt_pk_bf16_f32 v192, v164, v165
	v_cvt_pk_bf16_f32 v193, v166, v167
	v_cvt_pk_bf16_f32 v194, v168, v169
	v_cvt_pk_bf16_f32 v195, v170, v171
	v_lshl_add_u64 v[210:211], v[198:199], 1, s[14:15]
	global_store_dwordx4 v[210:211], v[188:191], off
	global_store_dwordx4 v[210:211], v[192:195], off offset:256
	v_mul_f32_e32 v157, v157, v157
	v_mul_f32_e32 v159, v159, v159
	v_mul_f32_e32 v161, v161, v161
	v_mul_f32_e32 v163, v163, v163
	v_mul_f32_e32 v165, v165, v165
	v_mul_f32_e32 v167, v167, v167
	v_mul_f32_e32 v169, v169, v169
	v_mul_f32_e32 v171, v171, v171
	v_fmac_f32_e32 v157, v156, v156
	v_fmac_f32_e32 v159, v158, v158
	v_fmac_f32_e32 v161, v160, v160
	v_fmac_f32_e32 v163, v162, v162
	v_fmac_f32_e32 v165, v164, v164
	v_fmac_f32_e32 v167, v166, v166
	v_fmac_f32_e32 v169, v168, v168
	v_fmac_f32_e32 v171, v170, v170
	v_add_f32_e32 v156, v157, v159
	v_add_f32_e32 v158, v161, v163
	v_add_f32_e32 v164, v165, v167
	v_add_f32_e32 v166, v169, v171
	v_add_f32_e32 v156, v156, v158
	v_add_f32_e32 v164, v164, v166
	v_add_f32_e32 v212, v156, v164
	v_mov_b32_e32 v213, v212
	s_nop 1
	v_permlane16_swap_b32_e32 v212, v213
	v_add_f32_e32 v212, v212, v213
	v_mov_b32_e32 v213, v212
	s_nop 1
	v_permlane32_swap_b32_e32 v212, v213
	s_and_saveexec_b64 s[26:27], s[2:3]
	v_lshlrev_b64 v[214:215], 6, v[206:207]
	v_lshl_add_u64 v[214:215], s[16:17], 0, v[214:215]
	v_lshl_add_u64 v[214:215], s[24:25], 2, v[214:215]
	v_lshl_add_u64 v[214:215], v[214:215], 0, s[8:9]
	v_add_f32_e32 v212, v212, v213
	global_store_dword v[214:215], v212, off
	s_or_b64 exec, exec, s[26:27]
	v_add_u32_e32 v206, 0xb0, v148
	v_ashrrev_i32_e32 v207, 31, v206
	v_lshlrev_b64 v[198:199], 10, v[206:207]
	v_lshl_add_u64 v[198:199], v[198:199], 0, v[146:147]
	v_lshl_add_u64 v[208:209], v[198:199], 1, s[12:13]
	global_load_dwordx4 v[180:183], v[208:209], off
	global_load_dwordx4 v[184:187], v[208:209], off offset:256
	s_waitcnt vmcnt(5)
	v_lshlrev_b32_e32 v156, 16, v172
	v_and_b32_e32 v157, 0xffff0000, v172
	v_lshlrev_b32_e32 v158, 16, v173
	v_and_b32_e32 v159, 0xffff0000, v173
	v_lshlrev_b32_e32 v160, 16, v174
	v_and_b32_e32 v161, 0xffff0000, v174
	v_lshlrev_b32_e32 v162, 16, v175
	v_and_b32_e32 v163, 0xffff0000, v175
	v_lshlrev_b32_e32 v164, 16, v176
	v_and_b32_e32 v165, 0xffff0000, v176
	v_lshlrev_b32_e32 v166, 16, v177
	v_and_b32_e32 v167, 0xffff0000, v177
	v_lshlrev_b32_e32 v168, 16, v178
	v_and_b32_e32 v169, 0xffff0000, v178
	v_lshlrev_b32_e32 v170, 16, v179
	v_and_b32_e32 v171, 0xffff0000, v179
	v_pk_add_f32 v[156:157], v[28:29], v[156:157]
	v_pk_add_f32 v[158:159], v[30:31], v[158:159]
	v_pk_add_f32 v[160:161], v[24:25], v[160:161]
	v_pk_add_f32 v[162:163], v[26:27], v[162:163]
	v_pk_add_f32 v[164:165], v[20:21], v[164:165]
	v_pk_add_f32 v[166:167], v[22:23], v[166:167]
	v_pk_add_f32 v[168:169], v[16:17], v[168:169]
	v_pk_add_f32 v[170:171], v[18:19], v[170:171]
	v_cvt_pk_bf16_f32 v188, v156, v157
	v_cvt_pk_bf16_f32 v189, v158, v159
	v_cvt_pk_bf16_f32 v190, v160, v161
	v_cvt_pk_bf16_f32 v191, v162, v163
	v_cvt_pk_bf16_f32 v192, v164, v165
	v_cvt_pk_bf16_f32 v193, v166, v167
	v_cvt_pk_bf16_f32 v194, v168, v169
	v_cvt_pk_bf16_f32 v195, v170, v171
	v_lshl_add_u64 v[210:211], v[196:197], 1, s[14:15]
	global_store_dwordx4 v[210:211], v[188:191], off
	global_store_dwordx4 v[210:211], v[192:195], off offset:256
	v_mul_f32_e32 v157, v157, v157
	v_mul_f32_e32 v159, v159, v159
	v_mul_f32_e32 v161, v161, v161
	v_mul_f32_e32 v163, v163, v163
	v_mul_f32_e32 v165, v165, v165
	v_mul_f32_e32 v167, v167, v167
	v_mul_f32_e32 v169, v169, v169
	v_mul_f32_e32 v171, v171, v171
	v_fmac_f32_e32 v157, v156, v156
	v_fmac_f32_e32 v159, v158, v158
	v_fmac_f32_e32 v161, v160, v160
	v_fmac_f32_e32 v163, v162, v162
	v_fmac_f32_e32 v165, v164, v164
	v_fmac_f32_e32 v167, v166, v166
	v_fmac_f32_e32 v169, v168, v168
	v_fmac_f32_e32 v171, v170, v170
	v_add_f32_e32 v156, v157, v159
	v_add_f32_e32 v158, v161, v163
	v_add_f32_e32 v164, v165, v167
	v_add_f32_e32 v166, v169, v171
	v_add_f32_e32 v156, v156, v158
	v_add_f32_e32 v164, v164, v166
	v_add_f32_e32 v212, v156, v164
	v_mov_b32_e32 v213, v212
	s_nop 1
	v_permlane16_swap_b32_e32 v212, v213
	v_add_f32_e32 v212, v212, v213
	v_mov_b32_e32 v213, v212
	s_nop 1
	v_permlane32_swap_b32_e32 v212, v213
	s_and_saveexec_b64 s[26:27], s[2:3]
	v_lshlrev_b64 v[214:215], 6, v[204:205]
	v_lshl_add_u64 v[214:215], s[16:17], 0, v[214:215]
	v_lshl_add_u64 v[214:215], s[24:25], 2, v[214:215]
	v_lshl_add_u64 v[214:215], v[214:215], 0, s[8:9]
	v_add_f32_e32 v212, v212, v213
	global_store_dword v[214:215], v212, off
	s_or_b64 exec, exec, s[26:27]
	s_waitcnt vmcnt(3)
	v_lshlrev_b32_e32 v156, 16, v180
	v_and_b32_e32 v157, 0xffff0000, v180
	v_lshlrev_b32_e32 v158, 16, v181
	v_and_b32_e32 v159, 0xffff0000, v181
	v_lshlrev_b32_e32 v160, 16, v182
	v_and_b32_e32 v161, 0xffff0000, v182
	v_lshlrev_b32_e32 v162, 16, v183
	v_and_b32_e32 v163, 0xffff0000, v183
	v_lshlrev_b32_e32 v164, 16, v184
	v_and_b32_e32 v165, 0xffff0000, v184
	v_lshlrev_b32_e32 v166, 16, v185
	v_and_b32_e32 v167, 0xffff0000, v185
	v_lshlrev_b32_e32 v168, 16, v186
	v_and_b32_e32 v169, 0xffff0000, v186
	v_lshlrev_b32_e32 v170, 16, v187
	v_and_b32_e32 v171, 0xffff0000, v187
	v_pk_add_f32 v[156:157], v[12:13], v[156:157]
	v_pk_add_f32 v[158:159], v[14:15], v[158:159]
	v_pk_add_f32 v[160:161], v[8:9], v[160:161]
	v_pk_add_f32 v[162:163], v[10:11], v[162:163]
	v_pk_add_f32 v[164:165], v[4:5], v[164:165]
	v_pk_add_f32 v[166:167], v[6:7], v[166:167]
	v_pk_add_f32 v[168:169], v[0:1], v[168:169]
	v_pk_add_f32 v[170:171], v[2:3], v[170:171]
	v_cvt_pk_bf16_f32 v188, v156, v157
	v_cvt_pk_bf16_f32 v189, v158, v159
	v_cvt_pk_bf16_f32 v190, v160, v161
	v_cvt_pk_bf16_f32 v191, v162, v163
	v_cvt_pk_bf16_f32 v192, v164, v165
	v_cvt_pk_bf16_f32 v193, v166, v167
	v_cvt_pk_bf16_f32 v194, v168, v169
	v_cvt_pk_bf16_f32 v195, v170, v171
	v_lshl_add_u64 v[210:211], v[198:199], 1, s[14:15]
	global_store_dwordx4 v[210:211], v[188:191], off
	global_store_dwordx4 v[210:211], v[192:195], off offset:256
	v_mul_f32_e32 v157, v157, v157
	v_mul_f32_e32 v159, v159, v159
	v_mul_f32_e32 v161, v161, v161
	v_mul_f32_e32 v163, v163, v163
	v_mul_f32_e32 v165, v165, v165
	v_mul_f32_e32 v167, v167, v167
	v_mul_f32_e32 v169, v169, v169
	v_mul_f32_e32 v171, v171, v171
	v_fmac_f32_e32 v157, v156, v156
	v_fmac_f32_e32 v159, v158, v158
	v_fmac_f32_e32 v161, v160, v160
	v_fmac_f32_e32 v163, v162, v162
	v_fmac_f32_e32 v165, v164, v164
	v_fmac_f32_e32 v167, v166, v166
	v_fmac_f32_e32 v169, v168, v168
	v_fmac_f32_e32 v171, v170, v170
	v_add_f32_e32 v156, v157, v159
	v_add_f32_e32 v158, v161, v163
	v_add_f32_e32 v164, v165, v167
	v_add_f32_e32 v166, v169, v171
	v_add_f32_e32 v156, v156, v158
	v_add_f32_e32 v164, v164, v166
	v_add_f32_e32 v212, v156, v164
	v_mov_b32_e32 v213, v212
	s_nop 1
	v_permlane16_swap_b32_e32 v212, v213
	v_add_f32_e32 v212, v212, v213
	v_mov_b32_e32 v213, v212
	s_nop 1
	v_permlane32_swap_b32_e32 v212, v213
	s_and_saveexec_b64 s[26:27], s[2:3]
	v_lshlrev_b64 v[214:215], 6, v[206:207]
	v_lshl_add_u64 v[214:215], s[16:17], 0, v[214:215]
	v_lshl_add_u64 v[214:215], s[24:25], 2, v[214:215]
	v_lshl_add_u64 v[214:215], v[214:215], 0, s[8:9]
	v_add_f32_e32 v212, v212, v213
	global_store_dword v[214:215], v212, off
	s_or_b64 exec, exec, s[26:27]
